# v9 (non-leader workgroups poll the cross-XCD release word) + HGRN2 local-state phase: 4 chunks unrolled on two register sets, each chunk's loads issued one chunk ahead
# speedup vs baseline: 1.0104x; 1.0104x over previous
; __device__ __forceinline__ unsigned xb_ld(unsigned* p)              { return __hip_atomic_load(p, __ATOMIC_RELAXED, __HIP_MEMORY_SCOPE_AGENT); }
; __device__ __forceinline__ unsigned xb_add(unsigned* p, unsigned v) { return __hip_atomic_fetch_add(p, v, __ATOMIC_RELAXED, __HIP_MEMORY_SCOPE_AGENT); }
; #define XB_SPIN(cond, bar) do { unsigned _sp = 0; while (cond) { __builtin_amdgcn_s_sleep(1); \
;     if ((++_sp & 255u) == 0u) { if (xb_ld(&(bar)[XB_TMO])) break; if (_sp > XB_SPIN_CAP) { atomicAdd(&(bar)[XB_TMO], 1u); break; } } } } while (0)
; __device__ __forceinline__ void xcd_barrier(const XcdBarrier& b) {
;     ...
;         const unsigned old = xb_add(&bar[XB_XSUB(b.x)], 1u);
;         const unsigned gen = old / nloc;
;         if (old + 1u == (gen + 1u) * nloc) {
;             __builtin_amdgcn_fence(__ATOMIC_RELEASE, "agent");
;             asm volatile("s_waitcnt vmcnt(0)" ::: "memory");
;             const unsigned og = xb_add(&bar[XB_TOP], 1u);
;             const unsigned tg = og / nx;
;             if (og + 1u == (tg + 1u) * nx) xb_add(&bar[XB_TOPGEN], 1u);
;             else XB_SPIN(xb_ld(&bar[XB_TOPGEN]) == tg, bar);
;             __builtin_amdgcn_fence(__ATOMIC_ACQUIRE, "agent");
;             xb_add(&bar[XB_XGEN(b.x)], 1u);
;             asm volatile("s_waitcnt vmcnt(0)" ::: "memory");
;         } else {
;             XB_SPIN(xb_ld(&bar[XB_XGEN(b.x)]) == gen, bar);
;             __builtin_amdgcn_fence(__ATOMIC_ACQUIRE, "agent");
;             asm volatile("s_waitcnt vmcnt(0)" ::: "memory");
;         }
.LBB0_118:
	s_or_b64 exec, exec, s[14:15]
	v_cvt_f32_u32_e32 v5, v3
	s_waitcnt vmcnt(0)
	v_readfirstlane_b32 s0, v4
	v_sub_u32_e32 v4, 0, v3
	v_rcp_iflag_f32_e32 v5, v5
	v_add_u32_e32 v6, s0, v2
	v_mul_f32_e32 v5, 0x4f7ffffe, v5
	v_cvt_u32_f32_e32 v5, v5
	v_mul_lo_u32 v2, v4, v5
	v_mul_hi_u32 v2, v5, v2
	v_add_u32_e32 v2, v5, v2
	v_mul_hi_u32 v2, v6, v2
	v_mul_lo_u32 v4, v2, v3
	v_sub_u32_e32 v4, v6, v4
	v_add_u32_e32 v5, 1, v2
	v_cmp_ge_u32_e32 vcc, v4, v3
	s_nop 1
	v_cndmask_b32_e32 v2, v2, v5, vcc
	v_sub_u32_e32 v5, v4, v3
	v_cndmask_b32_e32 v4, v4, v5, vcc
	v_add_u32_e32 v5, 1, v2
	v_cmp_ge_u32_e32 vcc, v4, v3
	v_add_u32_e32 v4, 1, v6
	s_nop 0
	v_cndmask_b32_e32 v2, v2, v5, vcc
	v_mul_lo_u32 v5, v3, v2
	v_add_u32_e32 v3, v5, v3
	v_cmp_ne_u32_e32 vcc, v4, v3
	s_and_saveexec_b64 s[0:1], vcc
	s_xor_b64 s[12:13], exec, s[0:1]
	s_cbranch_execz .LBB0_132
	s_waitcnt lgkmcnt(0)
	v_readlane_b32 s18, v255, 2
	v_readlane_b32 s19, v255, 3
	v_mov_b32_e32 v1, 0
	s_add_u32 s18, s18, 0x7500
	s_addc_u32 s19, s19, 0
	global_load_dword v1, v1, s[18:19] sc1
	s_waitcnt vmcnt(0)
	v_cmp_eq_u32_e32 vcc, v1, v2
	s_and_saveexec_b64 s[14:15], vcc
	s_cbranch_execz .LBB0_131
	v_readlane_b32 s0, v255, 2
	v_readlane_b32 s1, v255, 3
	s_add_u32 s16, s0, 0x4200
	s_addc_u32 s17, s1, 0
	s_mov_b32 s0, 1
	s_mov_b64 s[20:21], 0
	v_mov_b32_e32 v1, 0
	s_branch .LBB0_122

; template <bool OUT>
; __device__ __forceinline__ void hgrn_unit(int unit, LAS unsigned char* lds, const float* HLF, const bf16* HQ, const bf16* HV, const bf16* HG, bf16* MIX, float* UBUF, float* DTOT, const float* SST, gu32* rdy4 = nullptr) {
;     ...
;     for (int c = 0; c < 4; ++c) {
;         const int rows = row_base + 64 * c + 16 * tq;
;         float cs[16]; unsigned short vv[16], qq[16];
; #pragma unroll
;         for (int i = 0; i < 16; ++i) { cs[i] = HLF[(size_t)(rows + i) * 512 + col0 + kx]; vv[i] = HV[(size_t)(rows + i) * 512 + col0 + kx]; if (OUT) qq[i] = HQ[(size_t)(rows + i) * 512 + col0 + kx]; }
;         float lf[16];
; #pragma unroll
;         for (int i = 0; i < 16; ++i) { lf[i] = cs[i]; if (i) cs[i] += cs[i - 1]; }
.LBB0_467:
	s_movk_i32 s27, 0
	v_add_u32_e32 v38, s27, v45
	v_add_u32_e32 v66, 2, v38
	v_ashrrev_i32_e32 v39, 31, v38
	v_add_u32_e32 v56, 1, v38
	v_ashrrev_i32_e32 v67, 31, v66
	v_add_u32_e32 v70, 3, v38
	v_lshlrev_b64 v[52:53], 9, v[38:39]
	v_ashrrev_i32_e32 v57, 31, v56
	v_lshlrev_b64 v[66:67], 9, v[66:67]
	v_ashrrev_i32_e32 v71, 31, v70
	v_or_b32_e32 v52, v52, v34
	v_lshlrev_b64 v[56:57], 9, v[56:57]
	v_or_b32_e32 v66, v66, v34
	v_lshlrev_b64 v[70:71], 9, v[70:71]
	v_lshl_add_u64 v[54:55], v[52:53], 2, s[18:19]
	v_lshl_add_u64 v[52:53], v[52:53], 1, s[20:21]
	v_or_b32_e32 v56, v56, v34
	v_lshl_add_u64 v[68:69], v[66:67], 2, s[18:19]
	v_lshl_add_u64 v[66:67], v[66:67], 1, s[20:21]
	v_or_b32_e32 v70, v70, v34
	v_lshl_add_u64 v[60:61], v[56:57], 2, s[18:19]
	v_lshl_add_u64 v[56:57], v[56:57], 1, s[20:21]
	v_lshl_add_u64 v[72:73], v[70:71], 2, s[18:19]
	v_lshl_add_u64 v[70:71], v[70:71], 1, s[20:21]
	global_load_dword v50, v[54:55], off
	global_load_ushort v58, v[52:53], off
	global_load_dword v80, v[60:61], off
	global_load_ushort v81, v[56:57], off
	global_load_dword v82, v[68:69], off
	global_load_ushort v83, v[66:67], off
	global_load_dword v84, v[72:73], off
	global_load_ushort v85, v[70:71], off
	v_add_u32_e32 v52, 4, v38
	v_add_u32_e32 v66, 6, v38
	v_ashrrev_i32_e32 v53, 31, v52
	v_add_u32_e32 v56, 5, v38
	v_ashrrev_i32_e32 v67, 31, v66
	v_add_u32_e32 v70, 7, v38
	v_lshlrev_b64 v[52:53], 9, v[52:53]
	v_ashrrev_i32_e32 v57, 31, v56
	v_lshlrev_b64 v[66:67], 9, v[66:67]
	v_ashrrev_i32_e32 v71, 31, v70
	v_or_b32_e32 v52, v52, v34
	v_lshlrev_b64 v[56:57], 9, v[56:57]
	v_or_b32_e32 v66, v66, v34
	v_lshlrev_b64 v[70:71], 9, v[70:71]
	v_lshl_add_u64 v[54:55], v[52:53], 2, s[18:19]
	v_lshl_add_u64 v[52:53], v[52:53], 1, s[20:21]
	v_or_b32_e32 v56, v56, v34
	v_lshl_add_u64 v[68:69], v[66:67], 2, s[18:19]
	v_lshl_add_u64 v[66:67], v[66:67], 1, s[20:21]
	v_or_b32_e32 v70, v70, v34
	v_lshl_add_u64 v[60:61], v[56:57], 2, s[18:19]
	v_lshl_add_u64 v[56:57], v[56:57], 1, s[20:21]
	v_lshl_add_u64 v[72:73], v[70:71], 2, s[18:19]
	v_lshl_add_u64 v[70:71], v[70:71], 1, s[20:21]
	global_load_dword v86, v[54:55], off
	global_load_ushort v87, v[52:53], off
	global_load_dword v88, v[60:61], off
	global_load_ushort v89, v[56:57], off
	global_load_dword v90, v[68:69], off
	global_load_ushort v91, v[66:67], off
	global_load_dword v92, v[72:73], off
	global_load_ushort v93, v[70:71], off
	v_add_u32_e32 v52, 8, v38
	v_add_u32_e32 v66, 10, v38
	v_ashrrev_i32_e32 v53, 31, v52
	v_add_u32_e32 v56, 9, v38
	v_ashrrev_i32_e32 v67, 31, v66
	v_add_u32_e32 v70, 11, v38
	v_lshlrev_b64 v[52:53], 9, v[52:53]
	v_ashrrev_i32_e32 v57, 31, v56
	v_lshlrev_b64 v[66:67], 9, v[66:67]
	v_ashrrev_i32_e32 v71, 31, v70
	v_or_b32_e32 v52, v52, v34
	v_lshlrev_b64 v[56:57], 9, v[56:57]
	v_or_b32_e32 v66, v66, v34
	v_lshlrev_b64 v[70:71], 9, v[70:71]
	v_lshl_add_u64 v[54:55], v[52:53], 1, s[20:21]
	v_or_b32_e32 v56, v56, v34
	v_lshl_add_u64 v[68:69], v[66:67], 1, s[20:21]
	v_or_b32_e32 v70, v70, v34
	v_lshl_add_u64 v[60:61], v[56:57], 1, s[20:21]
	v_lshl_add_u64 v[72:73], v[70:71], 1, s[20:21]
	global_load_ushort v94, v[54:55], off
	global_load_ushort v95, v[60:61], off
	global_load_ushort v96, v[68:69], off
	global_load_ushort v97, v[72:73], off
	v_add_u32_e32 v54, 12, v38
	v_add_u32_e32 v68, 13, v38
	v_add_u32_e32 v74, 14, v38
	v_add_u32_e32 v38, 15, v38
	v_ashrrev_i32_e32 v55, 31, v54
	v_ashrrev_i32_e32 v75, 31, v74
	v_ashrrev_i32_e32 v39, 31, v38
	v_lshlrev_b64 v[54:55], 9, v[54:55]
	v_ashrrev_i32_e32 v69, 31, v68
	v_lshlrev_b64 v[74:75], 9, v[74:75]
	v_lshlrev_b64 v[38:39], 9, v[38:39]
	v_or_b32_e32 v54, v54, v34
	v_lshlrev_b64 v[68:69], 9, v[68:69]
	v_or_b32_e32 v74, v74, v34
	v_or_b32_e32 v38, v38, v34
	v_lshl_add_u64 v[60:61], v[54:55], 1, s[20:21]
	v_or_b32_e32 v68, v68, v34
	v_lshl_add_u64 v[76:77], v[74:75], 1, s[20:21]
	v_lshl_add_u64 v[78:79], v[38:39], 1, s[20:21]
	v_lshl_add_u64 v[52:53], v[52:53], 2, s[18:19]
	v_lshl_add_u64 v[72:73], v[68:69], 1, s[20:21]
	global_load_ushort v98, v[60:61], off
	global_load_ushort v99, v[72:73], off
	global_load_ushort v100, v[76:77], off
	global_load_ushort v101, v[78:79], off
	v_lshl_add_u64 v[56:57], v[56:57], 2, s[18:19]
	v_lshl_add_u64 v[60:61], v[66:67], 2, s[18:19]
	v_lshl_add_u64 v[66:67], v[70:71], 2, s[18:19]
	global_load_dword v76, v[52:53], off
	global_load_dword v77, v[56:57], off
	global_load_dword v78, v[60:61], off
	global_load_dword v79, v[66:67], off
	v_lshl_add_u64 v[52:53], v[54:55], 2, s[18:19]
	v_lshl_add_u64 v[54:55], v[68:69], 2, s[18:19]
	v_lshl_add_u64 v[56:57], v[74:75], 2, s[18:19]
	global_load_dword v102, v[52:53], off
	global_load_dword v103, v[54:55], off
	global_load_dword v104, v[56:57], off
	v_lshl_add_u64 v[38:39], v[38:39], 2, s[18:19]
	global_load_dword v105, v[38:39], off
	s_movk_i32 s27, 64
	v_add_u32_e32 v192, s27, v45
	v_add_u32_e32 v204, 2, v192
	v_ashrrev_i32_e32 v193, 31, v192
	v_add_u32_e32 v200, 1, v192
	v_ashrrev_i32_e32 v205, 31, v204
	v_add_u32_e32 v208, 3, v192
	v_lshlrev_b64 v[196:197], 9, v[192:193]
	v_ashrrev_i32_e32 v201, 31, v200
	v_lshlrev_b64 v[204:205], 9, v[204:205]
	v_ashrrev_i32_e32 v209, 31, v208
	v_or_b32_e32 v196, v196, v34
	v_lshlrev_b64 v[200:201], 9, v[200:201]
	v_or_b32_e32 v204, v204, v34
	v_lshlrev_b64 v[208:209], 9, v[208:209]
	v_lshl_add_u64 v[198:199], v[196:197], 2, s[18:19]
	v_lshl_add_u64 v[196:197], v[196:197], 1, s[20:21]
	v_or_b32_e32 v200, v200, v34
	v_lshl_add_u64 v[206:207], v[204:205], 2, s[18:19]
	v_lshl_add_u64 v[204:205], v[204:205], 1, s[20:21]
	v_or_b32_e32 v208, v208, v34
	v_lshl_add_u64 v[202:203], v[200:201], 2, s[18:19]
	v_lshl_add_u64 v[200:201], v[200:201], 1, s[20:21]
; #define LDS_SYNC() do { asm volatile("s_waitcnt lgkmcnt(0)" ::: "memory"); __builtin_amdgcn_s_barrier(); asm volatile("" ::: "memory"); } while (0)
; template <bool OUT>
; __device__ __forceinline__ void hgrn_unit(int unit, LAS unsigned char* lds, const float* HLF, const bf16* HQ, const bf16* HV, const bf16* HG, bf16* MIX, float* UBUF, float* DTOT, const float* SST, gu32* rdy4 = nullptr) {
;     ...
;     for (int c = 0; c < 4; ++c) {
;         const int rows = row_base + 64 * c + 16 * tq;
;         float cs[16]; unsigned short vv[16], qq[16];
; #pragma unroll
;         for (int i = 0; i < 16; ++i) { cs[i] = HLF[(size_t)(rows + i) * 512 + col0 + kx]; vv[i] = HV[(size_t)(rows + i) * 512 + col0 + kx]; if (OUT) qq[i] = HQ[(size_t)(rows + i) * 512 + col0 + kx]; }
;         float lf[16];
; #pragma unroll
;         for (int i = 0; i < 16; ++i) { lf[i] = cs[i]; if (i) cs[i] += cs[i - 1]; }
;         TOT[tq * 128 + kx] = cs[15];
;         LDS_SYNC();
;         float off = 0.f, blast = 0.f;
; #pragma unroll
;         for (int q = 0; q < 4; ++q) { const float t = TOT[q * 128 + kx]; if (q < tq) off += t; blast += t; }
	v_lshl_add_u64 v[210:211], v[208:209], 2, s[18:19]
	v_lshl_add_u64 v[208:209], v[208:209], 1, s[20:21]
	global_load_dword v194, v[198:199], off
	global_load_ushort v195, v[196:197], off
	global_load_dword v218, v[202:203], off
	global_load_ushort v219, v[200:201], off
	global_load_dword v220, v[206:207], off
	global_load_ushort v221, v[204:205], off
	global_load_dword v222, v[210:211], off
	global_load_ushort v223, v[208:209], off
	v_add_u32_e32 v196, 4, v192
	v_add_u32_e32 v204, 6, v192
	v_ashrrev_i32_e32 v197, 31, v196
	v_add_u32_e32 v200, 5, v192
	v_ashrrev_i32_e32 v205, 31, v204
	v_add_u32_e32 v208, 7, v192
	v_lshlrev_b64 v[196:197], 9, v[196:197]
	v_ashrrev_i32_e32 v201, 31, v200
	v_lshlrev_b64 v[204:205], 9, v[204:205]
	v_ashrrev_i32_e32 v209, 31, v208
	v_or_b32_e32 v196, v196, v34
	v_lshlrev_b64 v[200:201], 9, v[200:201]
	v_or_b32_e32 v204, v204, v34
	v_lshlrev_b64 v[208:209], 9, v[208:209]
	v_lshl_add_u64 v[198:199], v[196:197], 2, s[18:19]
	v_lshl_add_u64 v[196:197], v[196:197], 1, s[20:21]
	v_or_b32_e32 v200, v200, v34
	v_lshl_add_u64 v[206:207], v[204:205], 2, s[18:19]
	v_lshl_add_u64 v[204:205], v[204:205], 1, s[20:21]
	v_or_b32_e32 v208, v208, v34
	v_lshl_add_u64 v[202:203], v[200:201], 2, s[18:19]
	v_lshl_add_u64 v[200:201], v[200:201], 1, s[20:21]
	v_lshl_add_u64 v[210:211], v[208:209], 2, s[18:19]
	v_lshl_add_u64 v[208:209], v[208:209], 1, s[20:21]
	global_load_dword v224, v[198:199], off
	global_load_ushort v225, v[196:197], off
	global_load_dword v226, v[202:203], off
	global_load_ushort v227, v[200:201], off
	global_load_dword v232, v[206:207], off
	global_load_ushort v233, v[204:205], off
	global_load_dword v234, v[210:211], off
	global_load_ushort v235, v[208:209], off
	v_add_u32_e32 v196, 8, v192
	v_add_u32_e32 v204, 10, v192
	v_ashrrev_i32_e32 v197, 31, v196
	v_add_u32_e32 v200, 9, v192
	v_ashrrev_i32_e32 v205, 31, v204
	v_add_u32_e32 v208, 11, v192
	v_lshlrev_b64 v[196:197], 9, v[196:197]
	v_ashrrev_i32_e32 v201, 31, v200
	v_lshlrev_b64 v[204:205], 9, v[204:205]
	v_ashrrev_i32_e32 v209, 31, v208
	v_or_b32_e32 v196, v196, v34
	v_lshlrev_b64 v[200:201], 9, v[200:201]
	v_or_b32_e32 v204, v204, v34
	v_lshlrev_b64 v[208:209], 9, v[208:209]
	v_lshl_add_u64 v[198:199], v[196:197], 1, s[20:21]
	v_or_b32_e32 v200, v200, v34
	v_lshl_add_u64 v[206:207], v[204:205], 1, s[20:21]
	v_or_b32_e32 v208, v208, v34
	v_lshl_add_u64 v[202:203], v[200:201], 1, s[20:21]
	v_lshl_add_u64 v[210:211], v[208:209], 1, s[20:21]
	global_load_ushort v236, v[198:199], off
	global_load_ushort v237, v[202:203], off
	global_load_ushort v238, v[206:207], off
	global_load_ushort v239, v[210:211], off
	v_add_u32_e32 v198, 12, v192
	v_add_u32_e32 v206, 13, v192
	v_add_u32_e32 v212, 14, v192
	v_add_u32_e32 v192, 15, v192
	v_ashrrev_i32_e32 v199, 31, v198
	v_ashrrev_i32_e32 v213, 31, v212
	v_ashrrev_i32_e32 v193, 31, v192
	v_lshlrev_b64 v[198:199], 9, v[198:199]
	v_ashrrev_i32_e32 v207, 31, v206
	v_lshlrev_b64 v[212:213], 9, v[212:213]
	v_lshlrev_b64 v[192:193], 9, v[192:193]
	v_or_b32_e32 v198, v198, v34
	v_lshlrev_b64 v[206:207], 9, v[206:207]
	v_or_b32_e32 v212, v212, v34
	v_or_b32_e32 v192, v192, v34
	v_lshl_add_u64 v[202:203], v[198:199], 1, s[20:21]
	v_or_b32_e32 v206, v206, v34
	v_lshl_add_u64 v[214:215], v[212:213], 1, s[20:21]
	v_lshl_add_u64 v[216:217], v[192:193], 1, s[20:21]
	v_lshl_add_u64 v[196:197], v[196:197], 2, s[18:19]
	v_lshl_add_u64 v[210:211], v[206:207], 1, s[20:21]
	global_load_ushort v240, v[202:203], off
	global_load_ushort v241, v[210:211], off
	global_load_ushort v242, v[214:215], off
	global_load_ushort v243, v[216:217], off
	v_lshl_add_u64 v[200:201], v[200:201], 2, s[18:19]
	v_lshl_add_u64 v[202:203], v[204:205], 2, s[18:19]
	v_lshl_add_u64 v[204:205], v[208:209], 2, s[18:19]
	global_load_dword v214, v[196:197], off
	global_load_dword v215, v[200:201], off
	global_load_dword v216, v[202:203], off
	global_load_dword v217, v[204:205], off
	v_lshl_add_u64 v[196:197], v[198:199], 2, s[18:19]
	v_lshl_add_u64 v[198:199], v[206:207], 2, s[18:19]
	v_lshl_add_u64 v[200:201], v[212:213], 2, s[18:19]
	global_load_dword v244, v[196:197], off
	global_load_dword v245, v[198:199], off
	global_load_dword v246, v[200:201], off
	v_lshl_add_u64 v[192:193], v[192:193], 2, s[18:19]
	global_load_dword v247, v[192:193], off
	s_waitcnt vmcnt(60)
	v_lshl_or_b32 v52, v81, 16, v58
	v_add_f32_e32 v58, v50, v80
	v_mul_f32_e32 v38, 0x3fb8aa3b, v50
	v_mul_f32_e32 v39, 0x3fb8aa3b, v80
	v_exp_f32_e32 v38, v38
	v_exp_f32_e32 v39, v39
	s_waitcnt vmcnt(56)
	v_lshl_or_b32 v53, v85, 16, v83
	v_mul_f32_e32 v56, 0x3fb8aa3b, v82
	v_mul_f32_e32 v57, 0x3fb8aa3b, v84
	v_pk_add_f32 v[72:73], v[38:39], 1.0 op_sel_hi:[1,0] neg_lo:[1,0] neg_hi:[1,0]
	v_exp_f32_e32 v56, v56
	v_exp_f32_e32 v57, v57
	s_waitcnt vmcnt(55)
	v_mul_f32_e32 v60, 0x3fb8aa3b, v86
	v_pk_add_f32 v[56:57], v[56:57], 1.0 op_sel_hi:[1,0] neg_lo:[1,0] neg_hi:[1,0]
	s_waitcnt vmcnt(53)
	v_mul_f32_e32 v61, 0x3fb8aa3b, v88
	s_waitcnt vmcnt(52)
	v_lshl_or_b32 v54, v89, 16, v87
	v_add_f32_e32 v87, v58, v82
	v_add_f32_e32 v89, v87, v84
	s_waitcnt vmcnt(51)
	v_mul_f32_e32 v70, 0x3fb8aa3b, v90
	s_waitcnt vmcnt(48)
	v_lshl_or_b32 v55, v93, 16, v91
	v_add_f32_e32 v91, v89, v86
	v_add_f32_e32 v93, v91, v88
	v_mul_f32_e32 v71, 0x3fb8aa3b, v92
	v_exp_f32_e32 v70, v70
	v_exp_f32_e32 v71, v71
	v_exp_f32_e32 v60, v60
	v_exp_f32_e32 v61, v61
	v_pk_add_f32 v[74:75], v[70:71], 1.0 op_sel_hi:[1,0] neg_lo:[1,0] neg_hi:[1,0]
	v_pk_add_f32 v[60:61], v[60:61], 1.0 op_sel_hi:[1,0] neg_lo:[1,0] neg_hi:[1,0]
	s_waitcnt vmcnt(46)
	v_lshl_or_b32 v66, v95, 16, v94
	v_add_f32_e32 v94, v93, v90
	v_add_f32_e32 v95, v94, v92
	s_waitcnt vmcnt(44)
	v_lshl_or_b32 v67, v97, 16, v96
	s_waitcnt vmcnt(42)
	v_lshl_or_b32 v68, v99, 16, v98
	s_waitcnt vmcnt(40)
	v_lshl_or_b32 v69, v101, 16, v100
	s_waitcnt vmcnt(39)
	v_add_f32_e32 v96, v95, v76
	s_waitcnt vmcnt(38)
	v_add_f32_e32 v97, v96, v77
	s_waitcnt vmcnt(37)
	v_add_f32_e32 v98, v97, v78
	s_waitcnt vmcnt(36)
	v_add_f32_e32 v99, v98, v79
	v_mul_f32_e32 v71, 0x3fb8aa3b, v79
	s_waitcnt vmcnt(35)
	v_add_f32_e32 v100, v99, v102
	s_waitcnt vmcnt(34)
	v_add_f32_e32 v101, v100, v103
	s_waitcnt vmcnt(33)
	v_add_f32_e32 v106, v101, v104
	v_mul_f32_e32 v38, 0x3fb8aa3b, v76
	s_waitcnt vmcnt(32)
	v_add_f32_e32 v79, v106, v105
	ds_write_b32 v62, v79
	v_mul_f32_e32 v39, 0x3fb8aa3b, v77
	s_waitcnt lgkmcnt(0)
	s_barrier
; #define LAS __attribute__((address_space(3)))
; __device__ __forceinline__ unsigned f2bf(float f) { unsigned u = __builtin_bit_cast(unsigned, f); return (u + 0x7fffu + ((u >> 16) & 1u)) >> 16; }
; __device__ __forceinline__ unsigned pk2(float lo, float hi) { return pg8::cvt_pk_bf16(lo, hi); }
; __device__ __forceinline__ float ex2(float x) { return __builtin_amdgcn_exp2f(x); }
; __device__ __forceinline__ int crow(int r, int hi) { return (r & 3) + 8 * (r >> 2) + 4 * hi; }
; template <bool OUT>
; __device__ __forceinline__ void hgrn_unit(int unit, LAS unsigned char* lds, const float* HLF, const bf16* HQ, const bf16* HV, const bf16* HG, bf16* MIX, float* UBUF, float* DTOT, const float* SST, gu32* rdy4 = nullptr) {
;     ...
;         unsigned kew[8], vtw[8];
; #pragma unroll
;         for (int i = 0; i < 16; i += 2) {
;             float ke[2];
; #pragma unroll
;             for (int e = 0; e < 2; ++e) { const float bi = off + cs[i + e], kk = 1.0f - ex2(lf[i + e] * LOG2E_F); ke[e] = kk * ex2((blast - bi) * LOG2E_F);
;                 if (OUT) { QT[(16 * tq + i + e) * 136 + kx] = (bf16)f2bf(bf2f(qq[i + e]) * ex2(bi * LOG2E_F)); KI[(16 * tq + i + e) * 136 + kx] = (bf16)f2bf(kk * ex2(-bi * LOG2E_F)); } }
;             kew[i >> 1] = pk2(ke[0], ke[1]); vtw[i >> 1] = (unsigned)vv[i] | ((unsigned)vv[i + 1] << 16);
;         }
;         *(LAS v4u*)(KET + kx * 72 + 16 * tq) = (v4u){kew[0], kew[1], kew[2], kew[3]}; *(LAS v4u*)(KET + kx * 72 + 16 * tq + 8) = (v4u){kew[4], kew[5], kew[6], kew[7]};
;         *(LAS v4u*)(VT + kx * 72 + 16 * tq) = (v4u){vtw[0], vtw[1], vtw[2], vtw[3]}; *(LAS v4u*)(VT + kx * 72 + 16 * tq + 8) = (v4u){vtw[4], vtw[5], vtw[6], vtw[7]};
;         if (tq == 0) { DEC[kx] = ex2(blast * LOG2E_F); dacc += blast; }
;     ...
;             float dk[16];
; #pragma unroll
;             for (int r = 0; r < 16; ++r) dk[r] = DEC[32 * ki + crow(r, hi)];
; #pragma unroll
;             for (int j = 0; j < 2; ++j)
; #pragma unroll
;                 for (int r = 0; r < 16; ++r) S[j][r] *= dk[r];
; #pragma unroll
;             for (int ks = 0; ks < 4; ++ks) { const bf16x8 a = *(const LAS bf16x8*)(KET + (32 * ki + r32) * 72 + 16 * ks + 8 * hi);
; #pragma unroll
;                 for (int j = 0; j < 2; ++j) { const bf16x8 bb = *(const LAS bf16x8*)(VT + (32 * (vi0 + j) + r32) * 72 + 16 * ks + 8 * hi); S[j] = MFMA32(a, bb, S[j]); } }
;         }
	v_exp_f32_e32 v38, v38
	v_exp_f32_e32 v39, v39
	v_mul_f32_e32 v70, 0x3fb8aa3b, v78
	ds_read2st64_b32 v[80:81], v63 offset1:2
	v_exp_f32_e32 v70, v70
	v_exp_f32_e32 v71, v71
	v_pk_add_f32 v[82:83], v[38:39], 1.0 op_sel_hi:[1,0] neg_lo:[1,0] neg_hi:[1,0]
	ds_read2st64_b32 v[38:39], v63 offset0:4 offset1:6
	v_mul_f32_e32 v76, 0x3fb8aa3b, v102
	v_pk_add_f32 v[84:85], v[70:71], 1.0 op_sel_hi:[1,0] neg_lo:[1,0] neg_hi:[1,0]
	s_waitcnt lgkmcnt(1)
	v_add_f32_e32 v70, 0, v80
	v_cndmask_b32_e64 v71, v70, 0, s[8:9]
	v_add_f32_e32 v78, v81, v71
	v_cndmask_b32_e64 v71, v71, v78, s[10:11]
	s_waitcnt lgkmcnt(0)
	v_add_f32_e32 v78, v38, v71
	v_add_f32_e32 v70, v70, v81
	v_cndmask_b32_e64 v71, v71, v78, s[12:13]
	v_add_f32_e32 v78, v70, v38
	v_add_f32_e32 v38, v39, v71
	v_cndmask_b32_e64 v81, v71, v38, s[14:15]
	v_mov_b32_e32 v80, v39
	v_add_f32_e32 v50, v50, v81
	v_pk_add_f32 v[38:39], v[78:79], v[80:81]
	v_mul_f32_e32 v77, 0x3fb8aa3b, v103
	v_sub_f32_e32 v50, v38, v50
	v_mul_f32_e32 v50, 0x3fb8aa3b, v50
	v_exp_f32_e32 v70, v50
	v_add_f32_e32 v50, v58, v81
	v_sub_f32_e32 v50, v38, v50
	v_mul_f32_e32 v50, 0x3fb8aa3b, v50
	v_exp_f32_e32 v71, v50
	v_add_f32_e32 v50, v87, v81
	v_sub_f32_e32 v50, v38, v50
	v_mul_f32_e32 v50, 0x3fb8aa3b, v50
	v_exp_f32_e32 v78, v50
	v_add_f32_e32 v50, v89, v81
	v_sub_f32_e32 v50, v38, v50
	v_mul_f32_e32 v50, 0x3fb8aa3b, v50
	v_exp_f32_e32 v79, v50
	v_add_f32_e32 v50, v91, v81
	v_sub_f32_e32 v50, v38, v50
	v_mul_f32_e32 v50, 0x3fb8aa3b, v50
	v_pk_mul_f32 v[70:71], v[72:73], v[70:71]
	v_exp_f32_e32 v72, v50
	v_add_f32_e32 v50, v93, v81
	v_sub_f32_e32 v50, v38, v50
	v_mul_f32_e32 v50, 0x3fb8aa3b, v50
	v_exp_f32_e32 v73, v50
	v_add_f32_e32 v50, v94, v81
	v_sub_f32_e32 v50, v38, v50
	v_mul_f32_e32 v50, 0x3fb8aa3b, v50
	v_pk_mul_f32 v[56:57], v[56:57], v[78:79]
	v_exp_f32_e32 v78, v50
	v_add_f32_e32 v50, v95, v81
	v_sub_f32_e32 v50, v38, v50
	v_mul_f32_e32 v50, 0x3fb8aa3b, v50
	v_exp_f32_e32 v79, v50
	v_add_f32_e32 v50, v96, v81
	v_sub_f32_e32 v50, v38, v50
	v_mul_f32_e32 v50, 0x3fb8aa3b, v50
	v_cvt_pk_bf16_f32 v70, v70, v71
	v_cvt_pk_bf16_f32 v71, v56, v57
	v_pk_mul_f32 v[56:57], v[60:61], v[72:73]
	v_exp_f32_e32 v60, v50
	v_add_f32_e32 v50, v97, v81
	v_sub_f32_e32 v50, v38, v50
	v_mul_f32_e32 v50, 0x3fb8aa3b, v50
	v_exp_f32_e32 v61, v50
	v_add_f32_e32 v50, v98, v81
	v_sub_f32_e32 v50, v38, v50
	v_mul_f32_e32 v50, 0x3fb8aa3b, v50
	v_cvt_pk_bf16_f32 v72, v56, v57
	v_pk_mul_f32 v[56:57], v[74:75], v[78:79]
	v_exp_f32_e32 v78, v50
	v_add_f32_e32 v50, v99, v81
	v_sub_f32_e32 v50, v38, v50
	v_mul_f32_e32 v50, 0x3fb8aa3b, v50
	v_exp_f32_e32 v79, v50
	v_add_f32_e32 v50, v100, v81
	v_cvt_pk_bf16_f32 v73, v56, v57
	v_pk_mul_f32 v[56:57], v[82:83], v[60:61]
	v_sub_f32_e32 v50, v38, v50
	v_cvt_pk_bf16_f32 v74, v56, v57
	v_pk_mul_f32 v[56:57], v[84:85], v[78:79]
	v_mul_f32_e32 v50, 0x3fb8aa3b, v50
	v_cvt_pk_bf16_f32 v75, v56, v57
	v_exp_f32_e32 v56, v50
	v_add_f32_e32 v50, v101, v81
	v_sub_f32_e32 v50, v38, v50
	v_mul_f32_e32 v50, 0x3fb8aa3b, v50
	v_exp_f32_e32 v57, v50
	v_add_f32_e32 v50, v106, v81
	v_sub_f32_e32 v50, v38, v50
	v_exp_f32_e32 v76, v76
	v_exp_f32_e32 v77, v77
	v_mul_f32_e32 v50, 0x3fb8aa3b, v50
	v_mul_f32_e32 v86, 0x3fb8aa3b, v104
	v_exp_f32_e32 v60, v50
	v_mul_f32_e32 v50, 0x3fb8aa3b, v105
	v_sub_f32_e32 v39, v38, v39
	v_exp_f32_e32 v80, v86
	v_exp_f32_e32 v81, v50
	v_mul_f32_e32 v39, 0x3fb8aa3b, v39
	v_exp_f32_e32 v61, v39
	v_pk_add_f32 v[76:77], v[76:77], 1.0 op_sel_hi:[1,0] neg_lo:[1,0] neg_hi:[1,0]
	s_nop 0
	v_pk_mul_f32 v[56:57], v[76:77], v[56:57]
	s_nop 0
	v_cvt_pk_bf16_f32 v76, v56, v57
	v_pk_add_f32 v[56:57], v[80:81], 1.0 op_sel_hi:[1,0] neg_lo:[1,0] neg_hi:[1,0]
	s_nop 0
	v_pk_mul_f32 v[56:57], v[56:57], v[60:61]
	s_nop 0
	v_cvt_pk_bf16_f32 v77, v56, v57
	ds_write_b128 v64, v[70:73] offset:34816
	ds_write_b128 v64, v[74:77] offset:34832
	ds_write_b128 v64, v[52:55] offset:53248
	ds_write_b128 v64, v[66:69] offset:53264
	s_and_saveexec_b64 s[30:31], s[8:9]
	s_cbranch_execz .Lh2_st0
	v_mul_f32_e32 v39, 0x3fb8aa3b, v38
	v_exp_f32_e32 v39, v39
	v_add_f32_e32 v44, v44, v38
	ds_write_b32 v65, v39
.Lh2_st0:
	s_or_b64 exec, exec, s[30:31]
	s_waitcnt lgkmcnt(0)
	s_barrier
	ds_read_b128 v[52:55], v46
	ds_read_b128 v[66:69], v46 offset:32
	s_waitcnt lgkmcnt(1)
	v_pk_mul_f32 v[18:19], v[18:19], v[52:53]
	v_pk_mul_f32 v[2:3], v[2:3], v[52:53]
	v_pk_mul_f32 v[20:21], v[20:21], v[54:55]
	v_pk_mul_f32 v[4:5], v[4:5], v[54:55]
	ds_read_b128 v[52:55], v46 offset:64
	ds_read_b128 v[70:73], v46 offset:96
	ds_read_b128 v[74:77], v47 offset:34816
	ds_read_b128 v[78:81], v48 offset:53248
	s_waitcnt lgkmcnt(4)
	v_pk_mul_f32 v[22:23], v[22:23], v[66:67]
	v_pk_mul_f32 v[6:7], v[6:7], v[66:67]
	v_pk_mul_f32 v[24:25], v[24:25], v[68:69]
	s_waitcnt lgkmcnt(3)
	v_pk_mul_f32 v[26:27], v[26:27], v[52:53]
	v_pk_mul_f32 v[28:29], v[28:29], v[54:55]
	s_waitcnt lgkmcnt(2)
	v_pk_mul_f32 v[30:31], v[30:31], v[70:71]
	v_pk_mul_f32 v[32:33], v[32:33], v[72:73]
	ds_read_b128 v[82:85], v47 offset:34848
	ds_read_b128 v[86:89], v48 offset:53280
	v_pk_mul_f32 v[8:9], v[8:9], v[68:69]
	ds_read_b128 v[66:69], v49 offset:53248
	s_waitcnt lgkmcnt(3)
	v_mfma_f32_32x32x16_bf16 v[18:33], v[74:77], v[78:81], v[18:33]
	v_mul_f32_e64 v10, v10, v52
	v_mul_f32_e64 v11, v11, v53
	v_mul_f32_e64 v12, v12, v54
	v_mul_f32_e64 v13, v13, v55
	v_mul_f32_e64 v14, v14, v70
	v_mul_f32_e64 v15, v15, v71
	v_pk_mul_f32 v[16:17], v[16:17], v[72:73]
	ds_read_b128 v[52:55], v49 offset:53280
	s_waitcnt lgkmcnt(1)
	v_mfma_f32_32x32x16_bf16 v[2:17], v[74:77], v[66:69], v[2:17]
	v_mfma_f32_32x32x16_bf16 v[18:33], v[82:85], v[86:89], v[18:33]
	s_waitcnt lgkmcnt(0)
	v_mfma_f32_32x32x16_bf16 v[2:17], v[82:85], v[52:55], v[2:17]
	ds_read_b128 v[52:55], v47 offset:34880
	ds_read_b128 v[66:69], v48 offset:53312
	ds_read_b128 v[70:73], v47 offset:34912
	ds_read_b128 v[74:77], v48 offset:53344
	s_waitcnt lgkmcnt(2)
	v_mfma_f32_32x32x16_bf16 v[18:33], v[52:55], v[66:69], v[18:33]
	ds_read_b128 v[66:69], v49 offset:53312
	ds_read_b128 v[78:81], v49 offset:53344
	s_waitcnt lgkmcnt(0)
	s_barrier
; #define LAS __attribute__((address_space(3)))
; __device__ __forceinline__ int crow(int r, int hi) { return (r & 3) + 8 * (r >> 2) + 4 * hi; }
; #define MFMA32(a, b, c) __builtin_amdgcn_mfma_f32_32x32x16_bf16((a), (b), (c), 0, 0, 0)
; template <bool OUT>
; __device__ __forceinline__ void hgrn_unit(int unit, LAS unsigned char* lds, const float* HLF, const bf16* HQ, const bf16* HV, const bf16* HG, bf16* MIX, float* UBUF, float* DTOT, const float* SST, gu32* rdy4 = nullptr) {
;     ...
;     for (int c = 0; c < 4; ++c) {
;         const int rows = row_base + 64 * c + 16 * tq;
;         float cs[16]; unsigned short vv[16], qq[16];
; #pragma unroll
;         for (int i = 0; i < 16; ++i) { cs[i] = HLF[(size_t)(rows + i) * 512 + col0 + kx]; vv[i] = HV[(size_t)(rows + i) * 512 + col0 + kx]; if (OUT) qq[i] = HQ[(size_t)(rows + i) * 512 + col0 + kx]; }
;         float lf[16];
; #pragma unroll
;         for (int i = 0; i < 16; ++i) { lf[i] = cs[i]; if (i) cs[i] += cs[i - 1]; }
;     ...
;             float dk[16];
; #pragma unroll
;             for (int r = 0; r < 16; ++r) dk[r] = DEC[32 * ki + crow(r, hi)];
; #pragma unroll
;             for (int j = 0; j < 2; ++j)
; #pragma unroll
;                 for (int r = 0; r < 16; ++r) S[j][r] *= dk[r];
; #pragma unroll
;             for (int ks = 0; ks < 4; ++ks) { const bf16x8 a = *(const LAS bf16x8*)(KET + (32 * ki + r32) * 72 + 16 * ks + 8 * hi);
; #pragma unroll
;                 for (int j = 0; j < 2; ++j) { const bf16x8 bb = *(const LAS bf16x8*)(VT + (32 * (vi0 + j) + r32) * 72 + 16 * ks + 8 * hi); S[j] = MFMA32(a, bb, S[j]); } }
;         }
	s_waitcnt lgkmcnt(1)
	v_mfma_f32_32x32x16_bf16 v[2:17], v[52:55], v[66:69], v[2:17]
	v_mfma_f32_32x32x16_bf16 v[18:33], v[70:73], v[74:77], v[18:33]
	s_waitcnt lgkmcnt(0)
	v_mfma_f32_32x32x16_bf16 v[2:17], v[70:73], v[78:81], v[2:17]
	s_movk_i32 s27, 128
	v_add_u32_e32 v38, s27, v45
	v_add_u32_e32 v66, 2, v38
	v_ashrrev_i32_e32 v39, 31, v38
	v_add_u32_e32 v56, 1, v38
	v_ashrrev_i32_e32 v67, 31, v66
	v_add_u32_e32 v70, 3, v38
	v_lshlrev_b64 v[52:53], 9, v[38:39]
	v_ashrrev_i32_e32 v57, 31, v56
	v_lshlrev_b64 v[66:67], 9, v[66:67]
	v_ashrrev_i32_e32 v71, 31, v70
	v_or_b32_e32 v52, v52, v34
	v_lshlrev_b64 v[56:57], 9, v[56:57]
	v_or_b32_e32 v66, v66, v34
	v_lshlrev_b64 v[70:71], 9, v[70:71]
	v_lshl_add_u64 v[54:55], v[52:53], 2, s[18:19]
	v_lshl_add_u64 v[52:53], v[52:53], 1, s[20:21]
	v_or_b32_e32 v56, v56, v34
	v_lshl_add_u64 v[68:69], v[66:67], 2, s[18:19]
	v_lshl_add_u64 v[66:67], v[66:67], 1, s[20:21]
	v_or_b32_e32 v70, v70, v34
	v_lshl_add_u64 v[60:61], v[56:57], 2, s[18:19]
	v_lshl_add_u64 v[56:57], v[56:57], 1, s[20:21]
	v_lshl_add_u64 v[72:73], v[70:71], 2, s[18:19]
	v_lshl_add_u64 v[70:71], v[70:71], 1, s[20:21]
	global_load_dword v50, v[54:55], off
	global_load_ushort v58, v[52:53], off
	global_load_dword v80, v[60:61], off
	global_load_ushort v81, v[56:57], off
	global_load_dword v82, v[68:69], off
	global_load_ushort v83, v[66:67], off
	global_load_dword v84, v[72:73], off
	global_load_ushort v85, v[70:71], off
	v_add_u32_e32 v52, 4, v38
	v_add_u32_e32 v66, 6, v38
	v_ashrrev_i32_e32 v53, 31, v52
	v_add_u32_e32 v56, 5, v38
	v_ashrrev_i32_e32 v67, 31, v66
	v_add_u32_e32 v70, 7, v38
	v_lshlrev_b64 v[52:53], 9, v[52:53]
	v_ashrrev_i32_e32 v57, 31, v56
	v_lshlrev_b64 v[66:67], 9, v[66:67]
	v_ashrrev_i32_e32 v71, 31, v70
	v_or_b32_e32 v52, v52, v34
	v_lshlrev_b64 v[56:57], 9, v[56:57]
	v_or_b32_e32 v66, v66, v34
	v_lshlrev_b64 v[70:71], 9, v[70:71]
	v_lshl_add_u64 v[54:55], v[52:53], 2, s[18:19]
	v_lshl_add_u64 v[52:53], v[52:53], 1, s[20:21]
	v_or_b32_e32 v56, v56, v34
	v_lshl_add_u64 v[68:69], v[66:67], 2, s[18:19]
	v_lshl_add_u64 v[66:67], v[66:67], 1, s[20:21]
	v_or_b32_e32 v70, v70, v34
	v_lshl_add_u64 v[60:61], v[56:57], 2, s[18:19]
	v_lshl_add_u64 v[56:57], v[56:57], 1, s[20:21]
	v_lshl_add_u64 v[72:73], v[70:71], 2, s[18:19]
	v_lshl_add_u64 v[70:71], v[70:71], 1, s[20:21]
	global_load_dword v86, v[54:55], off
	global_load_ushort v87, v[52:53], off
	global_load_dword v88, v[60:61], off
	global_load_ushort v89, v[56:57], off
	global_load_dword v90, v[68:69], off
	global_load_ushort v91, v[66:67], off
	global_load_dword v92, v[72:73], off
	global_load_ushort v93, v[70:71], off
	v_add_u32_e32 v52, 8, v38
	v_add_u32_e32 v66, 10, v38
	v_ashrrev_i32_e32 v53, 31, v52
	v_add_u32_e32 v56, 9, v38
	v_ashrrev_i32_e32 v67, 31, v66
	v_add_u32_e32 v70, 11, v38
	v_lshlrev_b64 v[52:53], 9, v[52:53]
	v_ashrrev_i32_e32 v57, 31, v56
	v_lshlrev_b64 v[66:67], 9, v[66:67]
	v_ashrrev_i32_e32 v71, 31, v70
	v_or_b32_e32 v52, v52, v34
	v_lshlrev_b64 v[56:57], 9, v[56:57]
	v_or_b32_e32 v66, v66, v34
	v_lshlrev_b64 v[70:71], 9, v[70:71]
	v_lshl_add_u64 v[54:55], v[52:53], 1, s[20:21]
	v_or_b32_e32 v56, v56, v34
	v_lshl_add_u64 v[68:69], v[66:67], 1, s[20:21]
	v_or_b32_e32 v70, v70, v34
	v_lshl_add_u64 v[60:61], v[56:57], 1, s[20:21]
	v_lshl_add_u64 v[72:73], v[70:71], 1, s[20:21]
	global_load_ushort v94, v[54:55], off
	global_load_ushort v95, v[60:61], off
	global_load_ushort v96, v[68:69], off
	global_load_ushort v97, v[72:73], off
	v_add_u32_e32 v54, 12, v38
	v_add_u32_e32 v68, 13, v38
	v_add_u32_e32 v74, 14, v38
	v_add_u32_e32 v38, 15, v38
	v_ashrrev_i32_e32 v55, 31, v54
	v_ashrrev_i32_e32 v75, 31, v74
	v_ashrrev_i32_e32 v39, 31, v38
	v_lshlrev_b64 v[54:55], 9, v[54:55]
	v_ashrrev_i32_e32 v69, 31, v68
	v_lshlrev_b64 v[74:75], 9, v[74:75]
	v_lshlrev_b64 v[38:39], 9, v[38:39]
	v_or_b32_e32 v54, v54, v34
	v_lshlrev_b64 v[68:69], 9, v[68:69]
	v_or_b32_e32 v74, v74, v34
	v_or_b32_e32 v38, v38, v34
	v_lshl_add_u64 v[60:61], v[54:55], 1, s[20:21]
	v_or_b32_e32 v68, v68, v34
	v_lshl_add_u64 v[76:77], v[74:75], 1, s[20:21]
	v_lshl_add_u64 v[78:79], v[38:39], 1, s[20:21]
	v_lshl_add_u64 v[52:53], v[52:53], 2, s[18:19]
	v_lshl_add_u64 v[72:73], v[68:69], 1, s[20:21]
	global_load_ushort v98, v[60:61], off
	global_load_ushort v99, v[72:73], off
	global_load_ushort v100, v[76:77], off
	global_load_ushort v101, v[78:79], off
	v_lshl_add_u64 v[56:57], v[56:57], 2, s[18:19]
	v_lshl_add_u64 v[60:61], v[66:67], 2, s[18:19]
	v_lshl_add_u64 v[66:67], v[70:71], 2, s[18:19]
	global_load_dword v76, v[52:53], off
	global_load_dword v77, v[56:57], off
	global_load_dword v78, v[60:61], off
	global_load_dword v79, v[66:67], off
	v_lshl_add_u64 v[52:53], v[54:55], 2, s[18:19]
	v_lshl_add_u64 v[54:55], v[68:69], 2, s[18:19]
	v_lshl_add_u64 v[56:57], v[74:75], 2, s[18:19]
	global_load_dword v102, v[52:53], off
	global_load_dword v103, v[54:55], off
	global_load_dword v104, v[56:57], off
	v_lshl_add_u64 v[38:39], v[38:39], 2, s[18:19]
	global_load_dword v105, v[38:39], off
	s_waitcnt vmcnt(60)
	v_lshl_or_b32 v196, v219, 16, v195
	v_add_f32_e32 v195, v194, v218
	v_mul_f32_e32 v192, 0x3fb8aa3b, v194
	v_mul_f32_e32 v193, 0x3fb8aa3b, v218
	v_exp_f32_e32 v192, v192
	v_exp_f32_e32 v193, v193
	s_waitcnt vmcnt(56)
	v_lshl_or_b32 v197, v223, 16, v221
	v_mul_f32_e32 v200, 0x3fb8aa3b, v220
	v_mul_f32_e32 v201, 0x3fb8aa3b, v222
	v_pk_add_f32 v[210:211], v[192:193], 1.0 op_sel_hi:[1,0] neg_lo:[1,0] neg_hi:[1,0]
	v_exp_f32_e32 v200, v200
	v_exp_f32_e32 v201, v201
	s_waitcnt vmcnt(55)
	v_mul_f32_e32 v202, 0x3fb8aa3b, v224
	v_pk_add_f32 v[200:201], v[200:201], 1.0 op_sel_hi:[1,0] neg_lo:[1,0] neg_hi:[1,0]
	s_waitcnt vmcnt(53)
; #define LAS __attribute__((address_space(3)))
; #define LDS_SYNC() do { asm volatile("s_waitcnt lgkmcnt(0)" ::: "memory"); __builtin_amdgcn_s_barrier(); asm volatile("" ::: "memory"); } while (0)
; __device__ __forceinline__ unsigned f2bf(float f) { unsigned u = __builtin_bit_cast(unsigned, f); return (u + 0x7fffu + ((u >> 16) & 1u)) >> 16; }
; __device__ __forceinline__ unsigned pk2(float lo, float hi) { return pg8::cvt_pk_bf16(lo, hi); }
; __device__ __forceinline__ float ex2(float x) { return __builtin_amdgcn_exp2f(x); }
; template <bool OUT>
; __device__ __forceinline__ void hgrn_unit(int unit, LAS unsigned char* lds, const float* HLF, const bf16* HQ, const bf16* HV, const bf16* HG, bf16* MIX, float* UBUF, float* DTOT, const float* SST, gu32* rdy4 = nullptr) {
;     ...
;         for (int i = 0; i < 16; ++i) { lf[i] = cs[i]; if (i) cs[i] += cs[i - 1]; }
;         TOT[tq * 128 + kx] = cs[15];
;         LDS_SYNC();
;         float off = 0.f, blast = 0.f;
; #pragma unroll
;         for (int q = 0; q < 4; ++q) { const float t = TOT[q * 128 + kx]; if (q < tq) off += t; blast += t; }
;         unsigned kew[8], vtw[8];
; #pragma unroll
;         for (int i = 0; i < 16; i += 2) {
;             float ke[2];
; #pragma unroll
;             for (int e = 0; e < 2; ++e) { const float bi = off + cs[i + e], kk = 1.0f - ex2(lf[i + e] * LOG2E_F); ke[e] = kk * ex2((blast - bi) * LOG2E_F);
;                 if (OUT) { QT[(16 * tq + i + e) * 136 + kx] = (bf16)f2bf(bf2f(qq[i + e]) * ex2(bi * LOG2E_F)); KI[(16 * tq + i + e) * 136 + kx] = (bf16)f2bf(kk * ex2(-bi * LOG2E_F)); } }
;             kew[i >> 1] = pk2(ke[0], ke[1]); vtw[i >> 1] = (unsigned)vv[i] | ((unsigned)vv[i + 1] << 16);
;         }
;         *(LAS v4u*)(KET + kx * 72 + 16 * tq) = (v4u){kew[0], kew[1], kew[2], kew[3]}; *(LAS v4u*)(KET + kx * 72 + 16 * tq + 8) = (v4u){kew[4], kew[5], kew[6], kew[7]};
;         *(LAS v4u*)(VT + kx * 72 + 16 * tq) = (v4u){vtw[0], vtw[1], vtw[2], vtw[3]}; *(LAS v4u*)(VT + kx * 72 + 16 * tq + 8) = (v4u){vtw[4], vtw[5], vtw[6], vtw[7]};
;         if (tq == 0) { DEC[kx] = ex2(blast * LOG2E_F); dacc += blast; }
	v_mul_f32_e32 v203, 0x3fb8aa3b, v226
	s_waitcnt vmcnt(52)
	v_lshl_or_b32 v198, v227, 16, v225
	v_add_f32_e32 v225, v195, v220
	v_add_f32_e32 v227, v225, v222
	s_waitcnt vmcnt(51)
	v_mul_f32_e32 v208, 0x3fb8aa3b, v232
	s_waitcnt vmcnt(48)
	v_lshl_or_b32 v199, v235, 16, v233
	v_add_f32_e32 v233, v227, v224
	v_add_f32_e32 v235, v233, v226
	v_mul_f32_e32 v209, 0x3fb8aa3b, v234
	v_exp_f32_e32 v208, v208
	v_exp_f32_e32 v209, v209
	v_exp_f32_e32 v202, v202
	v_exp_f32_e32 v203, v203
	v_pk_add_f32 v[212:213], v[208:209], 1.0 op_sel_hi:[1,0] neg_lo:[1,0] neg_hi:[1,0]
	v_pk_add_f32 v[202:203], v[202:203], 1.0 op_sel_hi:[1,0] neg_lo:[1,0] neg_hi:[1,0]
	s_waitcnt vmcnt(46)
	v_lshl_or_b32 v204, v237, 16, v236
	v_add_f32_e32 v236, v235, v232
	v_add_f32_e32 v237, v236, v234
	s_waitcnt vmcnt(44)
	v_lshl_or_b32 v205, v239, 16, v238
	s_waitcnt vmcnt(42)
	v_lshl_or_b32 v206, v241, 16, v240
	s_waitcnt vmcnt(40)
	v_lshl_or_b32 v207, v243, 16, v242
	s_waitcnt vmcnt(39)
	v_add_f32_e32 v238, v237, v214
	s_waitcnt vmcnt(38)
	v_add_f32_e32 v239, v238, v215
	s_waitcnt vmcnt(37)
	v_add_f32_e32 v240, v239, v216
	s_waitcnt vmcnt(36)
	v_add_f32_e32 v241, v240, v217
	v_mul_f32_e32 v209, 0x3fb8aa3b, v217
	s_waitcnt vmcnt(35)
	v_add_f32_e32 v242, v241, v244
	s_waitcnt vmcnt(34)
	v_add_f32_e32 v243, v242, v245
	s_waitcnt vmcnt(33)
	v_add_f32_e32 v248, v243, v246
	v_mul_f32_e32 v192, 0x3fb8aa3b, v214
	s_waitcnt vmcnt(32)
	v_add_f32_e32 v217, v248, v247
	ds_write_b32 v62, v217
	v_mul_f32_e32 v193, 0x3fb8aa3b, v215
	s_waitcnt lgkmcnt(0)
	s_barrier
	v_exp_f32_e32 v192, v192
	v_exp_f32_e32 v193, v193
	v_mul_f32_e32 v208, 0x3fb8aa3b, v216
	ds_read2st64_b32 v[218:219], v63 offset1:2
	v_exp_f32_e32 v208, v208
	v_exp_f32_e32 v209, v209
	v_pk_add_f32 v[220:221], v[192:193], 1.0 op_sel_hi:[1,0] neg_lo:[1,0] neg_hi:[1,0]
	ds_read2st64_b32 v[192:193], v63 offset0:4 offset1:6
	v_mul_f32_e32 v214, 0x3fb8aa3b, v244
	v_pk_add_f32 v[222:223], v[208:209], 1.0 op_sel_hi:[1,0] neg_lo:[1,0] neg_hi:[1,0]
	s_waitcnt lgkmcnt(1)
	v_add_f32_e32 v208, 0, v218
	v_cndmask_b32_e64 v209, v208, 0, s[8:9]
	v_add_f32_e32 v216, v219, v209
	v_cndmask_b32_e64 v209, v209, v216, s[10:11]
	s_waitcnt lgkmcnt(0)
	v_add_f32_e32 v216, v192, v209
	v_add_f32_e32 v208, v208, v219
	v_cndmask_b32_e64 v209, v209, v216, s[12:13]
	v_add_f32_e32 v216, v208, v192
	v_add_f32_e32 v192, v193, v209
	v_cndmask_b32_e64 v219, v209, v192, s[14:15]
	v_mov_b32_e32 v218, v193
	v_add_f32_e32 v194, v194, v219
	v_pk_add_f32 v[192:193], v[216:217], v[218:219]
	v_mul_f32_e32 v215, 0x3fb8aa3b, v245
	v_sub_f32_e32 v194, v192, v194
	v_mul_f32_e32 v194, 0x3fb8aa3b, v194
	v_exp_f32_e32 v208, v194
	v_add_f32_e32 v194, v195, v219
	v_sub_f32_e32 v194, v192, v194
	v_mul_f32_e32 v194, 0x3fb8aa3b, v194
	v_exp_f32_e32 v209, v194
	v_add_f32_e32 v194, v225, v219
	v_sub_f32_e32 v194, v192, v194
	v_mul_f32_e32 v194, 0x3fb8aa3b, v194
	v_exp_f32_e32 v216, v194
	v_add_f32_e32 v194, v227, v219
	v_sub_f32_e32 v194, v192, v194
	v_mul_f32_e32 v194, 0x3fb8aa3b, v194
	v_exp_f32_e32 v217, v194
	v_add_f32_e32 v194, v233, v219
	v_sub_f32_e32 v194, v192, v194
	v_mul_f32_e32 v194, 0x3fb8aa3b, v194
	v_pk_mul_f32 v[208:209], v[210:211], v[208:209]
	v_exp_f32_e32 v210, v194
	v_add_f32_e32 v194, v235, v219
	v_sub_f32_e32 v194, v192, v194
	v_mul_f32_e32 v194, 0x3fb8aa3b, v194
	v_exp_f32_e32 v211, v194
	v_add_f32_e32 v194, v236, v219
	v_sub_f32_e32 v194, v192, v194
	v_mul_f32_e32 v194, 0x3fb8aa3b, v194
	v_pk_mul_f32 v[200:201], v[200:201], v[216:217]
	v_exp_f32_e32 v216, v194
	v_add_f32_e32 v194, v237, v219
	v_sub_f32_e32 v194, v192, v194
	v_mul_f32_e32 v194, 0x3fb8aa3b, v194
	v_exp_f32_e32 v217, v194
	v_add_f32_e32 v194, v238, v219
	v_sub_f32_e32 v194, v192, v194
	v_mul_f32_e32 v194, 0x3fb8aa3b, v194
	v_cvt_pk_bf16_f32 v208, v208, v209
	v_cvt_pk_bf16_f32 v209, v200, v201
	v_pk_mul_f32 v[200:201], v[202:203], v[210:211]
	v_exp_f32_e32 v202, v194
	v_add_f32_e32 v194, v239, v219
	v_sub_f32_e32 v194, v192, v194
	v_mul_f32_e32 v194, 0x3fb8aa3b, v194
	v_exp_f32_e32 v203, v194
	v_add_f32_e32 v194, v240, v219
	v_sub_f32_e32 v194, v192, v194
	v_mul_f32_e32 v194, 0x3fb8aa3b, v194
	v_cvt_pk_bf16_f32 v210, v200, v201
	v_pk_mul_f32 v[200:201], v[212:213], v[216:217]
	v_exp_f32_e32 v216, v194
	v_add_f32_e32 v194, v241, v219
	v_sub_f32_e32 v194, v192, v194
	v_mul_f32_e32 v194, 0x3fb8aa3b, v194
	v_exp_f32_e32 v217, v194
	v_add_f32_e32 v194, v242, v219
	v_cvt_pk_bf16_f32 v211, v200, v201
	v_pk_mul_f32 v[200:201], v[220:221], v[202:203]
	v_sub_f32_e32 v194, v192, v194
	v_cvt_pk_bf16_f32 v212, v200, v201
	v_pk_mul_f32 v[200:201], v[222:223], v[216:217]
	v_mul_f32_e32 v194, 0x3fb8aa3b, v194
	v_cvt_pk_bf16_f32 v213, v200, v201
	v_exp_f32_e32 v200, v194
	v_add_f32_e32 v194, v243, v219
	v_sub_f32_e32 v194, v192, v194
	v_mul_f32_e32 v194, 0x3fb8aa3b, v194
	v_exp_f32_e32 v201, v194
	v_add_f32_e32 v194, v248, v219
	v_sub_f32_e32 v194, v192, v194
	v_exp_f32_e32 v214, v214
	v_exp_f32_e32 v215, v215
	v_mul_f32_e32 v194, 0x3fb8aa3b, v194
	v_mul_f32_e32 v224, 0x3fb8aa3b, v246
	v_exp_f32_e32 v202, v194
	v_mul_f32_e32 v194, 0x3fb8aa3b, v247
	v_sub_f32_e32 v193, v192, v193
	v_exp_f32_e32 v218, v224
	v_exp_f32_e32 v219, v194
	v_mul_f32_e32 v193, 0x3fb8aa3b, v193
	v_exp_f32_e32 v203, v193
	v_pk_add_f32 v[214:215], v[214:215], 1.0 op_sel_hi:[1,0] neg_lo:[1,0] neg_hi:[1,0]
	s_nop 0
	v_pk_mul_f32 v[200:201], v[214:215], v[200:201]
	s_nop 0
	v_cvt_pk_bf16_f32 v214, v200, v201
	v_pk_add_f32 v[200:201], v[218:219], 1.0 op_sel_hi:[1,0] neg_lo:[1,0] neg_hi:[1,0]
	s_nop 0
	v_pk_mul_f32 v[200:201], v[200:201], v[202:203]
	s_nop 0
	v_cvt_pk_bf16_f32 v215, v200, v201
	ds_write_b128 v64, v[208:211] offset:34816
	ds_write_b128 v64, v[212:215] offset:34832
	ds_write_b128 v64, v[196:199] offset:53248
	ds_write_b128 v64, v[204:207] offset:53264
	s_and_saveexec_b64 s[30:31], s[8:9]
	s_cbranch_execz .Lh2_st1
	v_mul_f32_e32 v193, 0x3fb8aa3b, v192
	v_exp_f32_e32 v193, v193
	v_add_f32_e32 v44, v44, v192
	ds_write_b32 v65, v193
; #define LAS __attribute__((address_space(3)))
; __device__ __forceinline__ int crow(int r, int hi) { return (r & 3) + 8 * (r >> 2) + 4 * hi; }
; #define MFMA32(a, b, c) __builtin_amdgcn_mfma_f32_32x32x16_bf16((a), (b), (c), 0, 0, 0)
; template <bool OUT>
; __device__ __forceinline__ void hgrn_unit(int unit, LAS unsigned char* lds, const float* HLF, const bf16* HQ, const bf16* HV, const bf16* HG, bf16* MIX, float* UBUF, float* DTOT, const float* SST, gu32* rdy4 = nullptr) {
;     ...
;     for (int c = 0; c < 4; ++c) {
;         const int rows = row_base + 64 * c + 16 * tq;
;         float cs[16]; unsigned short vv[16], qq[16];
; #pragma unroll
;         for (int i = 0; i < 16; ++i) { cs[i] = HLF[(size_t)(rows + i) * 512 + col0 + kx]; vv[i] = HV[(size_t)(rows + i) * 512 + col0 + kx]; if (OUT) qq[i] = HQ[(size_t)(rows + i) * 512 + col0 + kx]; }
;         float lf[16];
; #pragma unroll
;         for (int i = 0; i < 16; ++i) { lf[i] = cs[i]; if (i) cs[i] += cs[i - 1]; }
;     ...
;             float dk[16];
; #pragma unroll
;             for (int r = 0; r < 16; ++r) dk[r] = DEC[32 * ki + crow(r, hi)];
; #pragma unroll
;             for (int j = 0; j < 2; ++j)
; #pragma unroll
;                 for (int r = 0; r < 16; ++r) S[j][r] *= dk[r];
; #pragma unroll
;             for (int ks = 0; ks < 4; ++ks) { const bf16x8 a = *(const LAS bf16x8*)(KET + (32 * ki + r32) * 72 + 16 * ks + 8 * hi);
; #pragma unroll
;                 for (int j = 0; j < 2; ++j) { const bf16x8 bb = *(const LAS bf16x8*)(VT + (32 * (vi0 + j) + r32) * 72 + 16 * ks + 8 * hi); S[j] = MFMA32(a, bb, S[j]); } }
;         }
.Lh2_st1:
	s_or_b64 exec, exec, s[30:31]
	s_waitcnt lgkmcnt(0)
	s_barrier
	ds_read_b128 v[196:199], v46
	ds_read_b128 v[204:207], v46 offset:32
	s_waitcnt lgkmcnt(1)
	v_pk_mul_f32 v[18:19], v[18:19], v[196:197]
	v_pk_mul_f32 v[2:3], v[2:3], v[196:197]
	v_pk_mul_f32 v[20:21], v[20:21], v[198:199]
	v_pk_mul_f32 v[4:5], v[4:5], v[198:199]
	ds_read_b128 v[196:199], v46 offset:64
	ds_read_b128 v[208:211], v46 offset:96
	ds_read_b128 v[212:215], v47 offset:34816
	ds_read_b128 v[216:219], v48 offset:53248
	s_waitcnt lgkmcnt(4)
	v_pk_mul_f32 v[22:23], v[22:23], v[204:205]
	v_pk_mul_f32 v[6:7], v[6:7], v[204:205]
	v_pk_mul_f32 v[24:25], v[24:25], v[206:207]
	s_waitcnt lgkmcnt(3)
	v_pk_mul_f32 v[26:27], v[26:27], v[196:197]
	v_pk_mul_f32 v[28:29], v[28:29], v[198:199]
	s_waitcnt lgkmcnt(2)
	v_pk_mul_f32 v[30:31], v[30:31], v[208:209]
	v_pk_mul_f32 v[32:33], v[32:33], v[210:211]
	ds_read_b128 v[220:223], v47 offset:34848
	ds_read_b128 v[224:227], v48 offset:53280
	v_pk_mul_f32 v[8:9], v[8:9], v[206:207]
	ds_read_b128 v[204:207], v49 offset:53248
	s_waitcnt lgkmcnt(3)
	v_mfma_f32_32x32x16_bf16 v[18:33], v[212:215], v[216:219], v[18:33]
	v_mul_f32_e64 v10, v10, v196
	v_mul_f32_e64 v11, v11, v197
	v_mul_f32_e64 v12, v12, v198
	v_mul_f32_e64 v13, v13, v199
	v_mul_f32_e64 v14, v14, v208
	v_mul_f32_e64 v15, v15, v209
	v_pk_mul_f32 v[16:17], v[16:17], v[210:211]
	ds_read_b128 v[196:199], v49 offset:53280
	s_waitcnt lgkmcnt(1)
	v_mfma_f32_32x32x16_bf16 v[2:17], v[212:215], v[204:207], v[2:17]
	v_mfma_f32_32x32x16_bf16 v[18:33], v[220:223], v[224:227], v[18:33]
	s_waitcnt lgkmcnt(0)
	v_mfma_f32_32x32x16_bf16 v[2:17], v[220:223], v[196:199], v[2:17]
	ds_read_b128 v[196:199], v47 offset:34880
	ds_read_b128 v[204:207], v48 offset:53312
	ds_read_b128 v[208:211], v47 offset:34912
	ds_read_b128 v[212:215], v48 offset:53344
	s_waitcnt lgkmcnt(2)
	v_mfma_f32_32x32x16_bf16 v[18:33], v[196:199], v[204:207], v[18:33]
	ds_read_b128 v[204:207], v49 offset:53312
	ds_read_b128 v[216:219], v49 offset:53344
	s_waitcnt lgkmcnt(0)
	s_barrier
	s_waitcnt lgkmcnt(1)
	v_mfma_f32_32x32x16_bf16 v[2:17], v[196:199], v[204:207], v[2:17]
	v_mfma_f32_32x32x16_bf16 v[18:33], v[208:211], v[212:215], v[18:33]
	s_waitcnt lgkmcnt(0)
	v_mfma_f32_32x32x16_bf16 v[2:17], v[208:211], v[216:219], v[2:17]
	s_movk_i32 s27, 192
	v_add_u32_e32 v192, s27, v45
	v_add_u32_e32 v204, 2, v192
	v_ashrrev_i32_e32 v193, 31, v192
	v_add_u32_e32 v200, 1, v192
	v_ashrrev_i32_e32 v205, 31, v204
	v_add_u32_e32 v208, 3, v192
	v_lshlrev_b64 v[196:197], 9, v[192:193]
	v_ashrrev_i32_e32 v201, 31, v200
	v_lshlrev_b64 v[204:205], 9, v[204:205]
	v_ashrrev_i32_e32 v209, 31, v208
	v_or_b32_e32 v196, v196, v34
	v_lshlrev_b64 v[200:201], 9, v[200:201]
	v_or_b32_e32 v204, v204, v34
	v_lshlrev_b64 v[208:209], 9, v[208:209]
	v_lshl_add_u64 v[198:199], v[196:197], 2, s[18:19]
	v_lshl_add_u64 v[196:197], v[196:197], 1, s[20:21]
	v_or_b32_e32 v200, v200, v34
	v_lshl_add_u64 v[206:207], v[204:205], 2, s[18:19]
	v_lshl_add_u64 v[204:205], v[204:205], 1, s[20:21]
	v_or_b32_e32 v208, v208, v34
	v_lshl_add_u64 v[202:203], v[200:201], 2, s[18:19]
	v_lshl_add_u64 v[200:201], v[200:201], 1, s[20:21]
	v_lshl_add_u64 v[210:211], v[208:209], 2, s[18:19]
	v_lshl_add_u64 v[208:209], v[208:209], 1, s[20:21]
	global_load_dword v194, v[198:199], off
	global_load_ushort v195, v[196:197], off
	global_load_dword v218, v[202:203], off
	global_load_ushort v219, v[200:201], off
	global_load_dword v220, v[206:207], off
	global_load_ushort v221, v[204:205], off
	global_load_dword v222, v[210:211], off
	global_load_ushort v223, v[208:209], off
	v_add_u32_e32 v196, 4, v192
	v_add_u32_e32 v204, 6, v192
	v_ashrrev_i32_e32 v197, 31, v196
	v_add_u32_e32 v200, 5, v192
	v_ashrrev_i32_e32 v205, 31, v204
	v_add_u32_e32 v208, 7, v192
	v_lshlrev_b64 v[196:197], 9, v[196:197]
	v_ashrrev_i32_e32 v201, 31, v200
	v_lshlrev_b64 v[204:205], 9, v[204:205]
	v_ashrrev_i32_e32 v209, 31, v208
	v_or_b32_e32 v196, v196, v34
	v_lshlrev_b64 v[200:201], 9, v[200:201]
	v_or_b32_e32 v204, v204, v34
	v_lshlrev_b64 v[208:209], 9, v[208:209]
	v_lshl_add_u64 v[198:199], v[196:197], 2, s[18:19]
	v_lshl_add_u64 v[196:197], v[196:197], 1, s[20:21]
	v_or_b32_e32 v200, v200, v34
	v_lshl_add_u64 v[206:207], v[204:205], 2, s[18:19]
	v_lshl_add_u64 v[204:205], v[204:205], 1, s[20:21]
	v_or_b32_e32 v208, v208, v34
	v_lshl_add_u64 v[202:203], v[200:201], 2, s[18:19]
	v_lshl_add_u64 v[200:201], v[200:201], 1, s[20:21]
	v_lshl_add_u64 v[210:211], v[208:209], 2, s[18:19]
	v_lshl_add_u64 v[208:209], v[208:209], 1, s[20:21]
	global_load_dword v224, v[198:199], off
	global_load_ushort v225, v[196:197], off
	global_load_dword v226, v[202:203], off
	global_load_ushort v227, v[200:201], off
	global_load_dword v232, v[206:207], off
	global_load_ushort v233, v[204:205], off
	global_load_dword v234, v[210:211], off
	global_load_ushort v235, v[208:209], off
	v_add_u32_e32 v196, 8, v192
	v_add_u32_e32 v204, 10, v192
	v_ashrrev_i32_e32 v197, 31, v196
	v_add_u32_e32 v200, 9, v192
	v_ashrrev_i32_e32 v205, 31, v204
	v_add_u32_e32 v208, 11, v192
	v_lshlrev_b64 v[196:197], 9, v[196:197]
	v_ashrrev_i32_e32 v201, 31, v200
	v_lshlrev_b64 v[204:205], 9, v[204:205]
	v_ashrrev_i32_e32 v209, 31, v208
	v_or_b32_e32 v196, v196, v34
	v_lshlrev_b64 v[200:201], 9, v[200:201]
	v_or_b32_e32 v204, v204, v34
	v_lshlrev_b64 v[208:209], 9, v[208:209]
	v_lshl_add_u64 v[198:199], v[196:197], 1, s[20:21]
	v_or_b32_e32 v200, v200, v34
	v_lshl_add_u64 v[206:207], v[204:205], 1, s[20:21]
	v_or_b32_e32 v208, v208, v34
	v_lshl_add_u64 v[202:203], v[200:201], 1, s[20:21]
	v_lshl_add_u64 v[210:211], v[208:209], 1, s[20:21]
; #define LDS_SYNC() do { asm volatile("s_waitcnt lgkmcnt(0)" ::: "memory"); __builtin_amdgcn_s_barrier(); asm volatile("" ::: "memory"); } while (0)
; template <bool OUT>
; __device__ __forceinline__ void hgrn_unit(int unit, LAS unsigned char* lds, const float* HLF, const bf16* HQ, const bf16* HV, const bf16* HG, bf16* MIX, float* UBUF, float* DTOT, const float* SST, gu32* rdy4 = nullptr) {
;     ...
;     for (int c = 0; c < 4; ++c) {
;         const int rows = row_base + 64 * c + 16 * tq;
;         float cs[16]; unsigned short vv[16], qq[16];
; #pragma unroll
;         for (int i = 0; i < 16; ++i) { cs[i] = HLF[(size_t)(rows + i) * 512 + col0 + kx]; vv[i] = HV[(size_t)(rows + i) * 512 + col0 + kx]; if (OUT) qq[i] = HQ[(size_t)(rows + i) * 512 + col0 + kx]; }
;         float lf[16];
; #pragma unroll
;         for (int i = 0; i < 16; ++i) { lf[i] = cs[i]; if (i) cs[i] += cs[i - 1]; }
;         TOT[tq * 128 + kx] = cs[15];
;         LDS_SYNC();
;         float off = 0.f, blast = 0.f;
; #pragma unroll
;         for (int q = 0; q < 4; ++q) { const float t = TOT[q * 128 + kx]; if (q < tq) off += t; blast += t; }
	global_load_ushort v236, v[198:199], off
	global_load_ushort v237, v[202:203], off
	global_load_ushort v238, v[206:207], off
	global_load_ushort v239, v[210:211], off
	v_add_u32_e32 v198, 12, v192
	v_add_u32_e32 v206, 13, v192
	v_add_u32_e32 v212, 14, v192
	v_add_u32_e32 v192, 15, v192
	v_ashrrev_i32_e32 v199, 31, v198
	v_ashrrev_i32_e32 v213, 31, v212
	v_ashrrev_i32_e32 v193, 31, v192
	v_lshlrev_b64 v[198:199], 9, v[198:199]
	v_ashrrev_i32_e32 v207, 31, v206
	v_lshlrev_b64 v[212:213], 9, v[212:213]
	v_lshlrev_b64 v[192:193], 9, v[192:193]
	v_or_b32_e32 v198, v198, v34
	v_lshlrev_b64 v[206:207], 9, v[206:207]
	v_or_b32_e32 v212, v212, v34
	v_or_b32_e32 v192, v192, v34
	v_lshl_add_u64 v[202:203], v[198:199], 1, s[20:21]
	v_or_b32_e32 v206, v206, v34
	v_lshl_add_u64 v[214:215], v[212:213], 1, s[20:21]
	v_lshl_add_u64 v[216:217], v[192:193], 1, s[20:21]
	v_lshl_add_u64 v[196:197], v[196:197], 2, s[18:19]
	v_lshl_add_u64 v[210:211], v[206:207], 1, s[20:21]
	global_load_ushort v240, v[202:203], off
	global_load_ushort v241, v[210:211], off
	global_load_ushort v242, v[214:215], off
	global_load_ushort v243, v[216:217], off
	v_lshl_add_u64 v[200:201], v[200:201], 2, s[18:19]
	v_lshl_add_u64 v[202:203], v[204:205], 2, s[18:19]
	v_lshl_add_u64 v[204:205], v[208:209], 2, s[18:19]
	global_load_dword v214, v[196:197], off
	global_load_dword v215, v[200:201], off
	global_load_dword v216, v[202:203], off
	global_load_dword v217, v[204:205], off
	v_lshl_add_u64 v[196:197], v[198:199], 2, s[18:19]
	v_lshl_add_u64 v[198:199], v[206:207], 2, s[18:19]
	v_lshl_add_u64 v[200:201], v[212:213], 2, s[18:19]
	global_load_dword v244, v[196:197], off
	global_load_dword v245, v[198:199], off
	global_load_dword v246, v[200:201], off
	v_lshl_add_u64 v[192:193], v[192:193], 2, s[18:19]
	global_load_dword v247, v[192:193], off
	s_waitcnt vmcnt(60)
	v_lshl_or_b32 v52, v81, 16, v58
	v_add_f32_e32 v58, v50, v80
	v_mul_f32_e32 v38, 0x3fb8aa3b, v50
	v_mul_f32_e32 v39, 0x3fb8aa3b, v80
	v_exp_f32_e32 v38, v38
	v_exp_f32_e32 v39, v39
	s_waitcnt vmcnt(56)
	v_lshl_or_b32 v53, v85, 16, v83
	v_mul_f32_e32 v56, 0x3fb8aa3b, v82
	v_mul_f32_e32 v57, 0x3fb8aa3b, v84
	v_pk_add_f32 v[72:73], v[38:39], 1.0 op_sel_hi:[1,0] neg_lo:[1,0] neg_hi:[1,0]
	v_exp_f32_e32 v56, v56
	v_exp_f32_e32 v57, v57
	s_waitcnt vmcnt(55)
	v_mul_f32_e32 v60, 0x3fb8aa3b, v86
	v_pk_add_f32 v[56:57], v[56:57], 1.0 op_sel_hi:[1,0] neg_lo:[1,0] neg_hi:[1,0]
	s_waitcnt vmcnt(53)
	v_mul_f32_e32 v61, 0x3fb8aa3b, v88
	s_waitcnt vmcnt(52)
	v_lshl_or_b32 v54, v89, 16, v87
	v_add_f32_e32 v87, v58, v82
	v_add_f32_e32 v89, v87, v84
	s_waitcnt vmcnt(51)
	v_mul_f32_e32 v70, 0x3fb8aa3b, v90
	s_waitcnt vmcnt(48)
	v_lshl_or_b32 v55, v93, 16, v91
	v_add_f32_e32 v91, v89, v86
	v_add_f32_e32 v93, v91, v88
	v_mul_f32_e32 v71, 0x3fb8aa3b, v92
	v_exp_f32_e32 v70, v70
	v_exp_f32_e32 v71, v71
	v_exp_f32_e32 v60, v60
	v_exp_f32_e32 v61, v61
	v_pk_add_f32 v[74:75], v[70:71], 1.0 op_sel_hi:[1,0] neg_lo:[1,0] neg_hi:[1,0]
	v_pk_add_f32 v[60:61], v[60:61], 1.0 op_sel_hi:[1,0] neg_lo:[1,0] neg_hi:[1,0]
	s_waitcnt vmcnt(46)
	v_lshl_or_b32 v66, v95, 16, v94
	v_add_f32_e32 v94, v93, v90
	v_add_f32_e32 v95, v94, v92
	s_waitcnt vmcnt(44)
	v_lshl_or_b32 v67, v97, 16, v96
	s_waitcnt vmcnt(42)
	v_lshl_or_b32 v68, v99, 16, v98
	s_waitcnt vmcnt(40)
	v_lshl_or_b32 v69, v101, 16, v100
	s_waitcnt vmcnt(39)
	v_add_f32_e32 v96, v95, v76
	s_waitcnt vmcnt(38)
	v_add_f32_e32 v97, v96, v77
	s_waitcnt vmcnt(37)
	v_add_f32_e32 v98, v97, v78
	s_waitcnt vmcnt(36)
	v_add_f32_e32 v99, v98, v79
	v_mul_f32_e32 v71, 0x3fb8aa3b, v79
	s_waitcnt vmcnt(35)
	v_add_f32_e32 v100, v99, v102
	s_waitcnt vmcnt(34)
	v_add_f32_e32 v101, v100, v103
	s_waitcnt vmcnt(33)
	v_add_f32_e32 v106, v101, v104
	v_mul_f32_e32 v38, 0x3fb8aa3b, v76
	s_waitcnt vmcnt(32)
	v_add_f32_e32 v79, v106, v105
	ds_write_b32 v62, v79
	v_mul_f32_e32 v39, 0x3fb8aa3b, v77
	s_waitcnt lgkmcnt(0)
	s_barrier
	v_exp_f32_e32 v38, v38
	v_exp_f32_e32 v39, v39
	v_mul_f32_e32 v70, 0x3fb8aa3b, v78
	ds_read2st64_b32 v[80:81], v63 offset1:2
	v_exp_f32_e32 v70, v70
	v_exp_f32_e32 v71, v71
	v_pk_add_f32 v[82:83], v[38:39], 1.0 op_sel_hi:[1,0] neg_lo:[1,0] neg_hi:[1,0]
	ds_read2st64_b32 v[38:39], v63 offset0:4 offset1:6
	v_mul_f32_e32 v76, 0x3fb8aa3b, v102
	v_pk_add_f32 v[84:85], v[70:71], 1.0 op_sel_hi:[1,0] neg_lo:[1,0] neg_hi:[1,0]
	s_waitcnt lgkmcnt(1)
	v_add_f32_e32 v70, 0, v80
	v_cndmask_b32_e64 v71, v70, 0, s[8:9]
	v_add_f32_e32 v78, v81, v71
	v_cndmask_b32_e64 v71, v71, v78, s[10:11]
	s_waitcnt lgkmcnt(0)
; #define LAS __attribute__((address_space(3)))
; __device__ __forceinline__ unsigned f2bf(float f) { unsigned u = __builtin_bit_cast(unsigned, f); return (u + 0x7fffu + ((u >> 16) & 1u)) >> 16; }
; __device__ __forceinline__ unsigned pk2(float lo, float hi) { return pg8::cvt_pk_bf16(lo, hi); }
; __device__ __forceinline__ float ex2(float x) { return __builtin_amdgcn_exp2f(x); }
; __device__ __forceinline__ int crow(int r, int hi) { return (r & 3) + 8 * (r >> 2) + 4 * hi; }
; template <bool OUT>
; __device__ __forceinline__ void hgrn_unit(int unit, LAS unsigned char* lds, const float* HLF, const bf16* HQ, const bf16* HV, const bf16* HG, bf16* MIX, float* UBUF, float* DTOT, const float* SST, gu32* rdy4 = nullptr) {
;     ...
;         unsigned kew[8], vtw[8];
; #pragma unroll
;         for (int i = 0; i < 16; i += 2) {
;             float ke[2];
; #pragma unroll
;             for (int e = 0; e < 2; ++e) { const float bi = off + cs[i + e], kk = 1.0f - ex2(lf[i + e] * LOG2E_F); ke[e] = kk * ex2((blast - bi) * LOG2E_F);
;                 if (OUT) { QT[(16 * tq + i + e) * 136 + kx] = (bf16)f2bf(bf2f(qq[i + e]) * ex2(bi * LOG2E_F)); KI[(16 * tq + i + e) * 136 + kx] = (bf16)f2bf(kk * ex2(-bi * LOG2E_F)); } }
;             kew[i >> 1] = pk2(ke[0], ke[1]); vtw[i >> 1] = (unsigned)vv[i] | ((unsigned)vv[i + 1] << 16);
;         }
;         *(LAS v4u*)(KET + kx * 72 + 16 * tq) = (v4u){kew[0], kew[1], kew[2], kew[3]}; *(LAS v4u*)(KET + kx * 72 + 16 * tq + 8) = (v4u){kew[4], kew[5], kew[6], kew[7]};
;         *(LAS v4u*)(VT + kx * 72 + 16 * tq) = (v4u){vtw[0], vtw[1], vtw[2], vtw[3]}; *(LAS v4u*)(VT + kx * 72 + 16 * tq + 8) = (v4u){vtw[4], vtw[5], vtw[6], vtw[7]};
;         if (tq == 0) { DEC[kx] = ex2(blast * LOG2E_F); dacc += blast; }
;     ...
;             float dk[16];
; #pragma unroll
;             for (int r = 0; r < 16; ++r) dk[r] = DEC[32 * ki + crow(r, hi)];
; #pragma unroll
;             for (int j = 0; j < 2; ++j)
; #pragma unroll
;                 for (int r = 0; r < 16; ++r) S[j][r] *= dk[r];
; #pragma unroll
;             for (int ks = 0; ks < 4; ++ks) { const bf16x8 a = *(const LAS bf16x8*)(KET + (32 * ki + r32) * 72 + 16 * ks + 8 * hi);
; #pragma unroll
;                 for (int j = 0; j < 2; ++j) { const bf16x8 bb = *(const LAS bf16x8*)(VT + (32 * (vi0 + j) + r32) * 72 + 16 * ks + 8 * hi); S[j] = MFMA32(a, bb, S[j]); } }
;         }
	v_add_f32_e32 v78, v38, v71
	v_add_f32_e32 v70, v70, v81
	v_cndmask_b32_e64 v71, v71, v78, s[12:13]
	v_add_f32_e32 v78, v70, v38
	v_add_f32_e32 v38, v39, v71
	v_cndmask_b32_e64 v81, v71, v38, s[14:15]
	v_mov_b32_e32 v80, v39
	v_add_f32_e32 v50, v50, v81
	v_pk_add_f32 v[38:39], v[78:79], v[80:81]
	v_mul_f32_e32 v77, 0x3fb8aa3b, v103
	v_sub_f32_e32 v50, v38, v50
	v_mul_f32_e32 v50, 0x3fb8aa3b, v50
	v_exp_f32_e32 v70, v50
	v_add_f32_e32 v50, v58, v81
	v_sub_f32_e32 v50, v38, v50
	v_mul_f32_e32 v50, 0x3fb8aa3b, v50
	v_exp_f32_e32 v71, v50
	v_add_f32_e32 v50, v87, v81
	v_sub_f32_e32 v50, v38, v50
	v_mul_f32_e32 v50, 0x3fb8aa3b, v50
	v_exp_f32_e32 v78, v50
	v_add_f32_e32 v50, v89, v81
	v_sub_f32_e32 v50, v38, v50
	v_mul_f32_e32 v50, 0x3fb8aa3b, v50
	v_exp_f32_e32 v79, v50
	v_add_f32_e32 v50, v91, v81
	v_sub_f32_e32 v50, v38, v50
	v_mul_f32_e32 v50, 0x3fb8aa3b, v50
	v_pk_mul_f32 v[70:71], v[72:73], v[70:71]
	v_exp_f32_e32 v72, v50
	v_add_f32_e32 v50, v93, v81
	v_sub_f32_e32 v50, v38, v50
	v_mul_f32_e32 v50, 0x3fb8aa3b, v50
	v_exp_f32_e32 v73, v50
	v_add_f32_e32 v50, v94, v81
	v_sub_f32_e32 v50, v38, v50
	v_mul_f32_e32 v50, 0x3fb8aa3b, v50
	v_pk_mul_f32 v[56:57], v[56:57], v[78:79]
	v_exp_f32_e32 v78, v50
	v_add_f32_e32 v50, v95, v81
	v_sub_f32_e32 v50, v38, v50
	v_mul_f32_e32 v50, 0x3fb8aa3b, v50
	v_exp_f32_e32 v79, v50
	v_add_f32_e32 v50, v96, v81
	v_sub_f32_e32 v50, v38, v50
	v_mul_f32_e32 v50, 0x3fb8aa3b, v50
	v_cvt_pk_bf16_f32 v70, v70, v71
	v_cvt_pk_bf16_f32 v71, v56, v57
	v_pk_mul_f32 v[56:57], v[60:61], v[72:73]
	v_exp_f32_e32 v60, v50
	v_add_f32_e32 v50, v97, v81
	v_sub_f32_e32 v50, v38, v50
	v_mul_f32_e32 v50, 0x3fb8aa3b, v50
	v_exp_f32_e32 v61, v50
	v_add_f32_e32 v50, v98, v81
	v_sub_f32_e32 v50, v38, v50
	v_mul_f32_e32 v50, 0x3fb8aa3b, v50
	v_cvt_pk_bf16_f32 v72, v56, v57
	v_pk_mul_f32 v[56:57], v[74:75], v[78:79]
	v_exp_f32_e32 v78, v50
	v_add_f32_e32 v50, v99, v81
	v_sub_f32_e32 v50, v38, v50
	v_mul_f32_e32 v50, 0x3fb8aa3b, v50
	v_exp_f32_e32 v79, v50
	v_add_f32_e32 v50, v100, v81
	v_cvt_pk_bf16_f32 v73, v56, v57
	v_pk_mul_f32 v[56:57], v[82:83], v[60:61]
	v_sub_f32_e32 v50, v38, v50
	v_cvt_pk_bf16_f32 v74, v56, v57
	v_pk_mul_f32 v[56:57], v[84:85], v[78:79]
	v_mul_f32_e32 v50, 0x3fb8aa3b, v50
	v_cvt_pk_bf16_f32 v75, v56, v57
	v_exp_f32_e32 v56, v50
	v_add_f32_e32 v50, v101, v81
	v_sub_f32_e32 v50, v38, v50
	v_mul_f32_e32 v50, 0x3fb8aa3b, v50
	v_exp_f32_e32 v57, v50
	v_add_f32_e32 v50, v106, v81
	v_sub_f32_e32 v50, v38, v50
	v_exp_f32_e32 v76, v76
	v_exp_f32_e32 v77, v77
	v_mul_f32_e32 v50, 0x3fb8aa3b, v50
	v_mul_f32_e32 v86, 0x3fb8aa3b, v104
	v_exp_f32_e32 v60, v50
	v_mul_f32_e32 v50, 0x3fb8aa3b, v105
	v_sub_f32_e32 v39, v38, v39
	v_exp_f32_e32 v80, v86
	v_exp_f32_e32 v81, v50
	v_mul_f32_e32 v39, 0x3fb8aa3b, v39
	v_exp_f32_e32 v61, v39
	v_pk_add_f32 v[76:77], v[76:77], 1.0 op_sel_hi:[1,0] neg_lo:[1,0] neg_hi:[1,0]
	s_nop 0
	v_pk_mul_f32 v[56:57], v[76:77], v[56:57]
	s_nop 0
	v_cvt_pk_bf16_f32 v76, v56, v57
	v_pk_add_f32 v[56:57], v[80:81], 1.0 op_sel_hi:[1,0] neg_lo:[1,0] neg_hi:[1,0]
	s_nop 0
	v_pk_mul_f32 v[56:57], v[56:57], v[60:61]
	s_nop 0
	v_cvt_pk_bf16_f32 v77, v56, v57
	ds_write_b128 v64, v[70:73] offset:34816
	ds_write_b128 v64, v[74:77] offset:34832
	ds_write_b128 v64, v[52:55] offset:53248
	ds_write_b128 v64, v[66:69] offset:53264
	s_and_saveexec_b64 s[30:31], s[8:9]
	s_cbranch_execz .Lh2_st2
	v_mul_f32_e32 v39, 0x3fb8aa3b, v38
	v_exp_f32_e32 v39, v39
	v_add_f32_e32 v44, v44, v38
	ds_write_b32 v65, v39
.Lh2_st2:
	s_or_b64 exec, exec, s[30:31]
	s_waitcnt lgkmcnt(0)
	s_barrier
	ds_read_b128 v[52:55], v46
	ds_read_b128 v[66:69], v46 offset:32
	s_waitcnt lgkmcnt(1)
	v_pk_mul_f32 v[18:19], v[18:19], v[52:53]
	v_pk_mul_f32 v[2:3], v[2:3], v[52:53]
	v_pk_mul_f32 v[20:21], v[20:21], v[54:55]
	v_pk_mul_f32 v[4:5], v[4:5], v[54:55]
	ds_read_b128 v[52:55], v46 offset:64
	ds_read_b128 v[70:73], v46 offset:96
	ds_read_b128 v[74:77], v47 offset:34816
	ds_read_b128 v[78:81], v48 offset:53248
	s_waitcnt lgkmcnt(4)
	v_pk_mul_f32 v[22:23], v[22:23], v[66:67]
	v_pk_mul_f32 v[6:7], v[6:7], v[66:67]
	v_pk_mul_f32 v[24:25], v[24:25], v[68:69]
	s_waitcnt lgkmcnt(3)
	v_pk_mul_f32 v[26:27], v[26:27], v[52:53]
	v_pk_mul_f32 v[28:29], v[28:29], v[54:55]
	s_waitcnt lgkmcnt(2)
	v_pk_mul_f32 v[30:31], v[30:31], v[70:71]
	v_pk_mul_f32 v[32:33], v[32:33], v[72:73]
	ds_read_b128 v[82:85], v47 offset:34848
	ds_read_b128 v[86:89], v48 offset:53280
	v_pk_mul_f32 v[8:9], v[8:9], v[68:69]
	ds_read_b128 v[66:69], v49 offset:53248
	s_waitcnt lgkmcnt(3)
	v_mfma_f32_32x32x16_bf16 v[18:33], v[74:77], v[78:81], v[18:33]
	v_mul_f32_e64 v10, v10, v52
	v_mul_f32_e64 v11, v11, v53
	v_mul_f32_e64 v12, v12, v54
	v_mul_f32_e64 v13, v13, v55
	v_mul_f32_e64 v14, v14, v70
	v_mul_f32_e64 v15, v15, v71
	v_pk_mul_f32 v[16:17], v[16:17], v[72:73]
	ds_read_b128 v[52:55], v49 offset:53280
	s_waitcnt lgkmcnt(1)
	v_mfma_f32_32x32x16_bf16 v[2:17], v[74:77], v[66:69], v[2:17]
	v_mfma_f32_32x32x16_bf16 v[18:33], v[82:85], v[86:89], v[18:33]
	s_waitcnt lgkmcnt(0)
	v_mfma_f32_32x32x16_bf16 v[2:17], v[82:85], v[52:55], v[2:17]
	ds_read_b128 v[52:55], v47 offset:34880
	ds_read_b128 v[66:69], v48 offset:53312
	ds_read_b128 v[70:73], v47 offset:34912
	ds_read_b128 v[74:77], v48 offset:53344
	s_waitcnt lgkmcnt(2)
	v_mfma_f32_32x32x16_bf16 v[18:33], v[52:55], v[66:69], v[18:33]
	ds_read_b128 v[66:69], v49 offset:53312
	ds_read_b128 v[78:81], v49 offset:53344
	s_waitcnt lgkmcnt(0)
	s_barrier
; #define LAS __attribute__((address_space(3)))
; #define LDS_SYNC() do { asm volatile("s_waitcnt lgkmcnt(0)" ::: "memory"); __builtin_amdgcn_s_barrier(); asm volatile("" ::: "memory"); } while (0)
; __device__ __forceinline__ unsigned f2bf(float f) { unsigned u = __builtin_bit_cast(unsigned, f); return (u + 0x7fffu + ((u >> 16) & 1u)) >> 16; }
; __device__ __forceinline__ unsigned pk2(float lo, float hi) { return pg8::cvt_pk_bf16(lo, hi); }
; __device__ __forceinline__ float ex2(float x) { return __builtin_amdgcn_exp2f(x); }
; template <bool OUT>
; __device__ __forceinline__ void hgrn_unit(int unit, LAS unsigned char* lds, const float* HLF, const bf16* HQ, const bf16* HV, const bf16* HG, bf16* MIX, float* UBUF, float* DTOT, const float* SST, gu32* rdy4 = nullptr) {
;     ...
;         for (int i = 0; i < 16; ++i) { lf[i] = cs[i]; if (i) cs[i] += cs[i - 1]; }
;         TOT[tq * 128 + kx] = cs[15];
;         LDS_SYNC();
;         float off = 0.f, blast = 0.f;
; #pragma unroll
;         for (int q = 0; q < 4; ++q) { const float t = TOT[q * 128 + kx]; if (q < tq) off += t; blast += t; }
;         unsigned kew[8], vtw[8];
; #pragma unroll
;         for (int i = 0; i < 16; i += 2) {
;             float ke[2];
; #pragma unroll
;             for (int e = 0; e < 2; ++e) { const float bi = off + cs[i + e], kk = 1.0f - ex2(lf[i + e] * LOG2E_F); ke[e] = kk * ex2((blast - bi) * LOG2E_F);
;                 if (OUT) { QT[(16 * tq + i + e) * 136 + kx] = (bf16)f2bf(bf2f(qq[i + e]) * ex2(bi * LOG2E_F)); KI[(16 * tq + i + e) * 136 + kx] = (bf16)f2bf(kk * ex2(-bi * LOG2E_F)); } }
;             kew[i >> 1] = pk2(ke[0], ke[1]); vtw[i >> 1] = (unsigned)vv[i] | ((unsigned)vv[i + 1] << 16);
;         }
;         *(LAS v4u*)(KET + kx * 72 + 16 * tq) = (v4u){kew[0], kew[1], kew[2], kew[3]}; *(LAS v4u*)(KET + kx * 72 + 16 * tq + 8) = (v4u){kew[4], kew[5], kew[6], kew[7]};
;         *(LAS v4u*)(VT + kx * 72 + 16 * tq) = (v4u){vtw[0], vtw[1], vtw[2], vtw[3]}; *(LAS v4u*)(VT + kx * 72 + 16 * tq + 8) = (v4u){vtw[4], vtw[5], vtw[6], vtw[7]};
;         if (tq == 0) { DEC[kx] = ex2(blast * LOG2E_F); dacc += blast; }
	s_waitcnt lgkmcnt(1)
	v_mfma_f32_32x32x16_bf16 v[2:17], v[52:55], v[66:69], v[2:17]
	v_mfma_f32_32x32x16_bf16 v[18:33], v[70:73], v[74:77], v[18:33]
	s_waitcnt lgkmcnt(0)
	v_mfma_f32_32x32x16_bf16 v[2:17], v[70:73], v[78:81], v[2:17]
	s_waitcnt vmcnt(28)
	v_lshl_or_b32 v196, v219, 16, v195
	v_add_f32_e32 v195, v194, v218
	v_mul_f32_e32 v192, 0x3fb8aa3b, v194
	v_mul_f32_e32 v193, 0x3fb8aa3b, v218
	v_exp_f32_e32 v192, v192
	v_exp_f32_e32 v193, v193
	s_waitcnt vmcnt(24)
	v_lshl_or_b32 v197, v223, 16, v221
	v_mul_f32_e32 v200, 0x3fb8aa3b, v220
	v_mul_f32_e32 v201, 0x3fb8aa3b, v222
	v_pk_add_f32 v[210:211], v[192:193], 1.0 op_sel_hi:[1,0] neg_lo:[1,0] neg_hi:[1,0]
	v_exp_f32_e32 v200, v200
	v_exp_f32_e32 v201, v201
	s_waitcnt vmcnt(23)
	v_mul_f32_e32 v202, 0x3fb8aa3b, v224
	v_pk_add_f32 v[200:201], v[200:201], 1.0 op_sel_hi:[1,0] neg_lo:[1,0] neg_hi:[1,0]
	s_waitcnt vmcnt(21)
	v_mul_f32_e32 v203, 0x3fb8aa3b, v226
	s_waitcnt vmcnt(20)
	v_lshl_or_b32 v198, v227, 16, v225
	v_add_f32_e32 v225, v195, v220
	v_add_f32_e32 v227, v225, v222
	s_waitcnt vmcnt(19)
	v_mul_f32_e32 v208, 0x3fb8aa3b, v232
	s_waitcnt vmcnt(16)
	v_lshl_or_b32 v199, v235, 16, v233
	v_add_f32_e32 v233, v227, v224
	v_add_f32_e32 v235, v233, v226
	v_mul_f32_e32 v209, 0x3fb8aa3b, v234
	v_exp_f32_e32 v208, v208
	v_exp_f32_e32 v209, v209
	v_exp_f32_e32 v202, v202
	v_exp_f32_e32 v203, v203
	v_pk_add_f32 v[212:213], v[208:209], 1.0 op_sel_hi:[1,0] neg_lo:[1,0] neg_hi:[1,0]
	v_pk_add_f32 v[202:203], v[202:203], 1.0 op_sel_hi:[1,0] neg_lo:[1,0] neg_hi:[1,0]
	s_waitcnt vmcnt(14)
	v_lshl_or_b32 v204, v237, 16, v236
	v_add_f32_e32 v236, v235, v232
	v_add_f32_e32 v237, v236, v234
	s_waitcnt vmcnt(12)
	v_lshl_or_b32 v205, v239, 16, v238
	s_waitcnt vmcnt(10)
	v_lshl_or_b32 v206, v241, 16, v240
	s_waitcnt vmcnt(8)
	v_lshl_or_b32 v207, v243, 16, v242
	s_waitcnt vmcnt(7)
	v_add_f32_e32 v238, v237, v214
	s_waitcnt vmcnt(6)
	v_add_f32_e32 v239, v238, v215
	s_waitcnt vmcnt(5)
	v_add_f32_e32 v240, v239, v216
	s_waitcnt vmcnt(4)
	v_add_f32_e32 v241, v240, v217
	v_mul_f32_e32 v209, 0x3fb8aa3b, v217
	s_waitcnt vmcnt(3)
	v_add_f32_e32 v242, v241, v244
	s_waitcnt vmcnt(2)
	v_add_f32_e32 v243, v242, v245
	s_waitcnt vmcnt(1)
	v_add_f32_e32 v248, v243, v246
	v_mul_f32_e32 v192, 0x3fb8aa3b, v214
	s_waitcnt vmcnt(0)
	v_add_f32_e32 v217, v248, v247
	ds_write_b32 v62, v217
	v_mul_f32_e32 v193, 0x3fb8aa3b, v215
	s_waitcnt lgkmcnt(0)
	s_barrier
	v_exp_f32_e32 v192, v192
	v_exp_f32_e32 v193, v193
	v_mul_f32_e32 v208, 0x3fb8aa3b, v216
	ds_read2st64_b32 v[218:219], v63 offset1:2
	v_exp_f32_e32 v208, v208
	v_exp_f32_e32 v209, v209
	v_pk_add_f32 v[220:221], v[192:193], 1.0 op_sel_hi:[1,0] neg_lo:[1,0] neg_hi:[1,0]
	ds_read2st64_b32 v[192:193], v63 offset0:4 offset1:6
	v_mul_f32_e32 v214, 0x3fb8aa3b, v244
	v_pk_add_f32 v[222:223], v[208:209], 1.0 op_sel_hi:[1,0] neg_lo:[1,0] neg_hi:[1,0]
	s_waitcnt lgkmcnt(1)
	v_add_f32_e32 v208, 0, v218
	v_cndmask_b32_e64 v209, v208, 0, s[8:9]
	v_add_f32_e32 v216, v219, v209
	v_cndmask_b32_e64 v209, v209, v216, s[10:11]
	s_waitcnt lgkmcnt(0)
	v_add_f32_e32 v216, v192, v209
	v_add_f32_e32 v208, v208, v219
	v_cndmask_b32_e64 v209, v209, v216, s[12:13]
	v_add_f32_e32 v216, v208, v192
	v_add_f32_e32 v192, v193, v209
	v_cndmask_b32_e64 v219, v209, v192, s[14:15]
	v_mov_b32_e32 v218, v193
	v_add_f32_e32 v194, v194, v219
	v_pk_add_f32 v[192:193], v[216:217], v[218:219]
	v_mul_f32_e32 v215, 0x3fb8aa3b, v245
	v_sub_f32_e32 v194, v192, v194
	v_mul_f32_e32 v194, 0x3fb8aa3b, v194
	v_exp_f32_e32 v208, v194
	v_add_f32_e32 v194, v195, v219
	v_sub_f32_e32 v194, v192, v194
	v_mul_f32_e32 v194, 0x3fb8aa3b, v194
	v_exp_f32_e32 v209, v194
	v_add_f32_e32 v194, v225, v219
	v_sub_f32_e32 v194, v192, v194
	v_mul_f32_e32 v194, 0x3fb8aa3b, v194
	v_exp_f32_e32 v216, v194
	v_add_f32_e32 v194, v227, v219
	v_sub_f32_e32 v194, v192, v194
	v_mul_f32_e32 v194, 0x3fb8aa3b, v194
	v_exp_f32_e32 v217, v194
	v_add_f32_e32 v194, v233, v219
	v_sub_f32_e32 v194, v192, v194
	v_mul_f32_e32 v194, 0x3fb8aa3b, v194
	v_pk_mul_f32 v[208:209], v[210:211], v[208:209]
	v_exp_f32_e32 v210, v194
	v_add_f32_e32 v194, v235, v219
	v_sub_f32_e32 v194, v192, v194
	v_mul_f32_e32 v194, 0x3fb8aa3b, v194
	v_exp_f32_e32 v211, v194
	v_add_f32_e32 v194, v236, v219
	v_sub_f32_e32 v194, v192, v194
	v_mul_f32_e32 v194, 0x3fb8aa3b, v194
	v_pk_mul_f32 v[200:201], v[200:201], v[216:217]
	v_exp_f32_e32 v216, v194
	v_add_f32_e32 v194, v237, v219
	v_sub_f32_e32 v194, v192, v194
	v_mul_f32_e32 v194, 0x3fb8aa3b, v194
	v_exp_f32_e32 v217, v194
	v_add_f32_e32 v194, v238, v219
	v_sub_f32_e32 v194, v192, v194
	v_mul_f32_e32 v194, 0x3fb8aa3b, v194
	v_cvt_pk_bf16_f32 v208, v208, v209
	v_cvt_pk_bf16_f32 v209, v200, v201
	v_pk_mul_f32 v[200:201], v[202:203], v[210:211]
	v_exp_f32_e32 v202, v194
	v_add_f32_e32 v194, v239, v219
	v_sub_f32_e32 v194, v192, v194
	v_mul_f32_e32 v194, 0x3fb8aa3b, v194
	v_exp_f32_e32 v203, v194
	v_add_f32_e32 v194, v240, v219
	v_sub_f32_e32 v194, v192, v194
	v_mul_f32_e32 v194, 0x3fb8aa3b, v194
	v_cvt_pk_bf16_f32 v210, v200, v201
	v_pk_mul_f32 v[200:201], v[212:213], v[216:217]
	v_exp_f32_e32 v216, v194
	v_add_f32_e32 v194, v241, v219
	v_sub_f32_e32 v194, v192, v194
	v_mul_f32_e32 v194, 0x3fb8aa3b, v194
	v_exp_f32_e32 v217, v194
	v_add_f32_e32 v194, v242, v219
	v_cvt_pk_bf16_f32 v211, v200, v201
	v_pk_mul_f32 v[200:201], v[220:221], v[202:203]
	v_sub_f32_e32 v194, v192, v194
	v_cvt_pk_bf16_f32 v212, v200, v201
	v_pk_mul_f32 v[200:201], v[222:223], v[216:217]
	v_mul_f32_e32 v194, 0x3fb8aa3b, v194
	v_cvt_pk_bf16_f32 v213, v200, v201
	v_exp_f32_e32 v200, v194
	v_add_f32_e32 v194, v243, v219
	v_sub_f32_e32 v194, v192, v194
	v_mul_f32_e32 v194, 0x3fb8aa3b, v194
	v_exp_f32_e32 v201, v194
	v_add_f32_e32 v194, v248, v219
	v_sub_f32_e32 v194, v192, v194
	v_exp_f32_e32 v214, v214
	v_exp_f32_e32 v215, v215
	v_mul_f32_e32 v194, 0x3fb8aa3b, v194
	v_mul_f32_e32 v224, 0x3fb8aa3b, v246
	v_exp_f32_e32 v202, v194
	v_mul_f32_e32 v194, 0x3fb8aa3b, v247
	v_sub_f32_e32 v193, v192, v193
	v_exp_f32_e32 v218, v224
	v_exp_f32_e32 v219, v194
	v_mul_f32_e32 v193, 0x3fb8aa3b, v193
	v_exp_f32_e32 v203, v193
	v_pk_add_f32 v[214:215], v[214:215], 1.0 op_sel_hi:[1,0] neg_lo:[1,0] neg_hi:[1,0]
	s_nop 0
	v_pk_mul_f32 v[200:201], v[214:215], v[200:201]
	s_nop 0
	v_cvt_pk_bf16_f32 v214, v200, v201
	v_pk_add_f32 v[200:201], v[218:219], 1.0 op_sel_hi:[1,0] neg_lo:[1,0] neg_hi:[1,0]
	s_nop 0
	v_pk_mul_f32 v[200:201], v[200:201], v[202:203]
	s_nop 0
	v_cvt_pk_bf16_f32 v215, v200, v201
	ds_write_b128 v64, v[208:211] offset:34816
	ds_write_b128 v64, v[212:215] offset:34832
	ds_write_b128 v64, v[196:199] offset:53248
	ds_write_b128 v64, v[204:207] offset:53264
	s_and_saveexec_b64 s[30:31], s[8:9]
	s_cbranch_execz .Lh2_st3
	v_mul_f32_e32 v193, 0x3fb8aa3b, v192
	v_exp_f32_e32 v193, v193
	v_add_f32_e32 v44, v44, v192
	ds_write_b32 v65, v193
; #define LAS __attribute__((address_space(3)))
; __device__ __forceinline__ int crow(int r, int hi) { return (r & 3) + 8 * (r >> 2) + 4 * hi; }
; #define MFMA32(a, b, c) __builtin_amdgcn_mfma_f32_32x32x16_bf16((a), (b), (c), 0, 0, 0)
; template <bool OUT>
; __device__ __forceinline__ void hgrn_unit(int unit, LAS unsigned char* lds, const float* HLF, const bf16* HQ, const bf16* HV, const bf16* HG, bf16* MIX, float* UBUF, float* DTOT, const float* SST, gu32* rdy4 = nullptr) {
;     ...
;             float dk[16];
; #pragma unroll
;             for (int r = 0; r < 16; ++r) dk[r] = DEC[32 * ki + crow(r, hi)];
; #pragma unroll
;             for (int j = 0; j < 2; ++j)
; #pragma unroll
;                 for (int r = 0; r < 16; ++r) S[j][r] *= dk[r];
; #pragma unroll
;             for (int ks = 0; ks < 4; ++ks) { const bf16x8 a = *(const LAS bf16x8*)(KET + (32 * ki + r32) * 72 + 16 * ks + 8 * hi);
; #pragma unroll
;                 for (int j = 0; j < 2; ++j) { const bf16x8 bb = *(const LAS bf16x8*)(VT + (32 * (vi0 + j) + r32) * 72 + 16 * ks + 8 * hi); S[j] = MFMA32(a, bb, S[j]); } }
;         }
.Lh2_st3:
	s_or_b64 exec, exec, s[30:31]
	s_waitcnt lgkmcnt(0)
	s_barrier
	ds_read_b128 v[196:199], v46
	ds_read_b128 v[204:207], v46 offset:32
	s_waitcnt lgkmcnt(1)
	v_pk_mul_f32 v[18:19], v[18:19], v[196:197]
	v_pk_mul_f32 v[2:3], v[2:3], v[196:197]
	v_pk_mul_f32 v[20:21], v[20:21], v[198:199]
	v_pk_mul_f32 v[4:5], v[4:5], v[198:199]
	ds_read_b128 v[196:199], v46 offset:64
	ds_read_b128 v[208:211], v46 offset:96
	ds_read_b128 v[212:215], v47 offset:34816
	ds_read_b128 v[216:219], v48 offset:53248
	s_waitcnt lgkmcnt(4)
	v_pk_mul_f32 v[22:23], v[22:23], v[204:205]
	v_pk_mul_f32 v[6:7], v[6:7], v[204:205]
	v_pk_mul_f32 v[24:25], v[24:25], v[206:207]
	s_waitcnt lgkmcnt(3)
	v_pk_mul_f32 v[26:27], v[26:27], v[196:197]
	v_pk_mul_f32 v[28:29], v[28:29], v[198:199]
	s_waitcnt lgkmcnt(2)
	v_pk_mul_f32 v[30:31], v[30:31], v[208:209]
	v_pk_mul_f32 v[32:33], v[32:33], v[210:211]
	ds_read_b128 v[220:223], v47 offset:34848
	ds_read_b128 v[224:227], v48 offset:53280
	v_pk_mul_f32 v[8:9], v[8:9], v[206:207]
	ds_read_b128 v[204:207], v49 offset:53248
	s_waitcnt lgkmcnt(3)
	v_mfma_f32_32x32x16_bf16 v[18:33], v[212:215], v[216:219], v[18:33]
	v_mul_f32_e64 v10, v10, v196
	v_mul_f32_e64 v11, v11, v197
	v_mul_f32_e64 v12, v12, v198
	v_mul_f32_e64 v13, v13, v199
	v_mul_f32_e64 v14, v14, v208
	v_mul_f32_e64 v15, v15, v209
	v_pk_mul_f32 v[16:17], v[16:17], v[210:211]
	ds_read_b128 v[196:199], v49 offset:53280
	s_waitcnt lgkmcnt(1)
	v_mfma_f32_32x32x16_bf16 v[2:17], v[212:215], v[204:207], v[2:17]
	v_mfma_f32_32x32x16_bf16 v[18:33], v[220:223], v[224:227], v[18:33]
	s_waitcnt lgkmcnt(0)
	v_mfma_f32_32x32x16_bf16 v[2:17], v[220:223], v[196:199], v[2:17]
	ds_read_b128 v[196:199], v47 offset:34880
	ds_read_b128 v[204:207], v48 offset:53312
	ds_read_b128 v[208:211], v47 offset:34912
	ds_read_b128 v[212:215], v48 offset:53344
	s_waitcnt lgkmcnt(2)
	v_mfma_f32_32x32x16_bf16 v[18:33], v[196:199], v[204:207], v[18:33]
	ds_read_b128 v[204:207], v49 offset:53312
	ds_read_b128 v[216:219], v49 offset:53344
	s_waitcnt lgkmcnt(0)
	s_barrier
	s_waitcnt lgkmcnt(1)
	v_mfma_f32_32x32x16_bf16 v[2:17], v[196:199], v[204:207], v[2:17]
	v_mfma_f32_32x32x16_bf16 v[18:33], v[208:211], v[212:215], v[18:33]
	s_waitcnt lgkmcnt(0)
	v_mfma_f32_32x32x16_bf16 v[2:17], v[208:211], v[216:219], v[2:17]

; __device__ __forceinline__ unsigned xb_ld(unsigned* p)              { return __hip_atomic_load(p, __ATOMIC_RELAXED, __HIP_MEMORY_SCOPE_AGENT); }
; __device__ __forceinline__ unsigned xb_add(unsigned* p, unsigned v) { return __hip_atomic_fetch_add(p, v, __ATOMIC_RELAXED, __HIP_MEMORY_SCOPE_AGENT); }
; #define XB_SPIN(cond, bar) do { unsigned _sp = 0; while (cond) { __builtin_amdgcn_s_sleep(1); \
;     if ((++_sp & 255u) == 0u) { if (xb_ld(&(bar)[XB_TMO])) break; if (_sp > XB_SPIN_CAP) { atomicAdd(&(bar)[XB_TMO], 1u); break; } } } } while (0)
; __device__ __forceinline__ void xcd_barrier(const XcdBarrier& b) {
;     ...
;         const unsigned old = xb_add(&bar[XB_XSUB(b.x)], 1u);
;         const unsigned gen = old / nloc;
;         if (old + 1u == (gen + 1u) * nloc) {
;             __builtin_amdgcn_fence(__ATOMIC_RELEASE, "agent");
;             asm volatile("s_waitcnt vmcnt(0)" ::: "memory");
;             const unsigned og = xb_add(&bar[XB_TOP], 1u);
;             const unsigned tg = og / nx;
;             if (og + 1u == (tg + 1u) * nx) xb_add(&bar[XB_TOPGEN], 1u);
;             else XB_SPIN(xb_ld(&bar[XB_TOPGEN]) == tg, bar);
;             __builtin_amdgcn_fence(__ATOMIC_ACQUIRE, "agent");
;             xb_add(&bar[XB_XGEN(b.x)], 1u);
;             asm volatile("s_waitcnt vmcnt(0)" ::: "memory");
;         } else {
;             XB_SPIN(xb_ld(&bar[XB_XGEN(b.x)]) == gen, bar);
;             __builtin_amdgcn_fence(__ATOMIC_ACQUIRE, "agent");
;             asm volatile("s_waitcnt vmcnt(0)" ::: "memory");
;         }
.LBB0_489:
	s_or_b64 exec, exec, s[22:23]
	v_cvt_f32_u32_e32 v6, v4
	s_waitcnt vmcnt(0)
	v_readfirstlane_b32 s1, v5
	v_sub_u32_e32 v5, 0, v4
	v_rcp_iflag_f32_e32 v6, v6
	v_add_u32_e32 v7, s1, v3
	v_mul_f32_e32 v6, 0x4f7ffffe, v6
	v_cvt_u32_f32_e32 v6, v6
	v_mul_lo_u32 v3, v5, v6
	v_mul_hi_u32 v3, v6, v3
	v_add_u32_e32 v3, v6, v3
	v_mul_hi_u32 v3, v7, v3
	v_mul_lo_u32 v5, v3, v4
	v_sub_u32_e32 v5, v7, v5
	v_add_u32_e32 v6, 1, v3
	v_cmp_ge_u32_e32 vcc, v5, v4
	s_nop 1
	v_cndmask_b32_e32 v3, v3, v6, vcc
	v_sub_u32_e32 v6, v5, v4
	v_cndmask_b32_e32 v5, v5, v6, vcc
	v_add_u32_e32 v6, 1, v3
	v_cmp_ge_u32_e32 vcc, v5, v4
	v_add_u32_e32 v5, 1, v7
	s_nop 0
	v_cndmask_b32_e32 v3, v3, v6, vcc
	v_mul_lo_u32 v6, v4, v3
	v_add_u32_e32 v4, v6, v4
	v_cmp_ne_u32_e32 vcc, v5, v4
	s_and_saveexec_b64 s[2:3], vcc
	s_xor_b64 s[20:21], exec, s[2:3]
	s_cbranch_execz .LBB0_503
	s_waitcnt lgkmcnt(0)
	v_readlane_b32 s26, v255, 2
	v_readlane_b32 s27, v255, 3
	v_mov_b32_e32 v2, 0
	s_add_u32 s26, s26, 0x7500
	s_addc_u32 s27, s27, 0
	global_load_dword v2, v2, s[26:27] sc1
	s_waitcnt vmcnt(0)
	v_cmp_eq_u32_e32 vcc, v2, v3
	s_and_saveexec_b64 s[22:23], vcc
	s_cbranch_execz .LBB0_502
	v_readlane_b32 s2, v255, 2
	v_readlane_b32 s3, v255, 3
	s_add_u32 s24, s2, 0x4200
	s_addc_u32 s25, s3, 0
	s_mov_b32 s1, 1
	s_mov_b64 s[30:31], 0
	v_mov_b32_e32 v2, 0
	s_branch .LBB0_493

; __device__ __forceinline__ unsigned xb_ld(unsigned* p)              { return __hip_atomic_load(p, __ATOMIC_RELAXED, __HIP_MEMORY_SCOPE_AGENT); }
; __device__ __forceinline__ unsigned xb_add(unsigned* p, unsigned v) { return __hip_atomic_fetch_add(p, v, __ATOMIC_RELAXED, __HIP_MEMORY_SCOPE_AGENT); }
; #define XB_SPIN(cond, bar) do { unsigned _sp = 0; while (cond) { __builtin_amdgcn_s_sleep(1); \
;     if ((++_sp & 255u) == 0u) { if (xb_ld(&(bar)[XB_TMO])) break; if (_sp > XB_SPIN_CAP) { atomicAdd(&(bar)[XB_TMO], 1u); break; } } } } while (0)
; __device__ __forceinline__ void xcd_barrier(const XcdBarrier& b) {
;     ...
;         const unsigned old = xb_add(&bar[XB_XSUB(b.x)], 1u);
;         const unsigned gen = old / nloc;
;         if (old + 1u == (gen + 1u) * nloc) {
;             __builtin_amdgcn_fence(__ATOMIC_RELEASE, "agent");
;             asm volatile("s_waitcnt vmcnt(0)" ::: "memory");
;             const unsigned og = xb_add(&bar[XB_TOP], 1u);
;             const unsigned tg = og / nx;
;             if (og + 1u == (tg + 1u) * nx) xb_add(&bar[XB_TOPGEN], 1u);
;             else XB_SPIN(xb_ld(&bar[XB_TOPGEN]) == tg, bar);
;             __builtin_amdgcn_fence(__ATOMIC_ACQUIRE, "agent");
;             xb_add(&bar[XB_XGEN(b.x)], 1u);
;             asm volatile("s_waitcnt vmcnt(0)" ::: "memory");
;         } else {
;             XB_SPIN(xb_ld(&bar[XB_XGEN(b.x)]) == gen, bar);
;             __builtin_amdgcn_fence(__ATOMIC_ACQUIRE, "agent");
;             asm volatile("s_waitcnt vmcnt(0)" ::: "memory");
;         }
.LBB0_1115:
	s_or_b64 exec, exec, s[10:11]
	v_cvt_f32_u32_e32 v5, v3
	s_waitcnt vmcnt(0)
	v_readfirstlane_b32 s0, v4
	v_sub_u32_e32 v4, 0, v3
	v_rcp_iflag_f32_e32 v5, v5
	v_add_u32_e32 v6, s0, v2
	v_mul_f32_e32 v5, 0x4f7ffffe, v5
	v_cvt_u32_f32_e32 v5, v5
	v_mul_lo_u32 v2, v4, v5
	v_mul_hi_u32 v2, v5, v2
	v_add_u32_e32 v2, v5, v2
	v_mul_hi_u32 v2, v6, v2
	v_mul_lo_u32 v4, v2, v3
	v_sub_u32_e32 v4, v6, v4
	v_add_u32_e32 v5, 1, v2
	v_cmp_ge_u32_e32 vcc, v4, v3
	s_nop 1
	v_cndmask_b32_e32 v2, v2, v5, vcc
	v_sub_u32_e32 v5, v4, v3
	v_cndmask_b32_e32 v4, v4, v5, vcc
	v_add_u32_e32 v5, 1, v2
	v_cmp_ge_u32_e32 vcc, v4, v3
	v_add_u32_e32 v4, 1, v6
	s_nop 0
	v_cndmask_b32_e32 v2, v2, v5, vcc
	v_mul_lo_u32 v5, v3, v2
	v_add_u32_e32 v3, v5, v3
	v_cmp_ne_u32_e32 vcc, v4, v3
	s_and_saveexec_b64 s[0:1], vcc
	s_xor_b64 s[8:9], exec, s[0:1]
	s_cbranch_execz .LBB0_1129
	s_waitcnt lgkmcnt(0)
	v_readlane_b32 s14, v255, 2
	v_readlane_b32 s15, v255, 3
	v_mov_b32_e32 v1, 0
	s_add_u32 s14, s14, 0x7500
	s_addc_u32 s15, s15, 0
	global_load_dword v1, v1, s[14:15] sc1
	s_waitcnt vmcnt(0)
	v_cmp_eq_u32_e32 vcc, v1, v2
	s_and_saveexec_b64 s[10:11], vcc
	s_cbranch_execz .LBB0_1128
	v_readlane_b32 s0, v255, 2
	v_readlane_b32 s1, v255, 3
	s_add_u32 s12, s0, 0x4200
	s_addc_u32 s13, s1, 0
	s_mov_b32 s0, 1
	s_mov_b64 s[16:17], 0
	v_mov_b32_e32 v1, 0
	s_branch .LBB0_1119

; __device__ __forceinline__ unsigned xb_ld(unsigned* p)              { return __hip_atomic_load(p, __ATOMIC_RELAXED, __HIP_MEMORY_SCOPE_AGENT); }
; __device__ __forceinline__ unsigned xb_add(unsigned* p, unsigned v) { return __hip_atomic_fetch_add(p, v, __ATOMIC_RELAXED, __HIP_MEMORY_SCOPE_AGENT); }
; #define XB_SPIN(cond, bar) do { unsigned _sp = 0; while (cond) { __builtin_amdgcn_s_sleep(1); \
;     if ((++_sp & 255u) == 0u) { if (xb_ld(&(bar)[XB_TMO])) break; if (_sp > XB_SPIN_CAP) { atomicAdd(&(bar)[XB_TMO], 1u); break; } } } } while (0)
; __device__ __forceinline__ void xcd_barrier(const XcdBarrier& b) {
;     ...
;         const unsigned old = xb_add(&bar[XB_XSUB(b.x)], 1u);
;         const unsigned gen = old / nloc;
;         if (old + 1u == (gen + 1u) * nloc) {
;             __builtin_amdgcn_fence(__ATOMIC_RELEASE, "agent");
;             asm volatile("s_waitcnt vmcnt(0)" ::: "memory");
;             const unsigned og = xb_add(&bar[XB_TOP], 1u);
;             const unsigned tg = og / nx;
;             if (og + 1u == (tg + 1u) * nx) xb_add(&bar[XB_TOPGEN], 1u);
;             else XB_SPIN(xb_ld(&bar[XB_TOPGEN]) == tg, bar);
;             __builtin_amdgcn_fence(__ATOMIC_ACQUIRE, "agent");
;             xb_add(&bar[XB_XGEN(b.x)], 1u);
;             asm volatile("s_waitcnt vmcnt(0)" ::: "memory");
;         } else {
;             XB_SPIN(xb_ld(&bar[XB_XGEN(b.x)]) == gen, bar);
;             __builtin_amdgcn_fence(__ATOMIC_ACQUIRE, "agent");
;             asm volatile("s_waitcnt vmcnt(0)" ::: "memory");
;         }
.LBB0_1206:
	s_or_b64 exec, exec, s[8:9]
	v_cvt_f32_u32_e32 v5, v3
	s_waitcnt vmcnt(0)
	v_readfirstlane_b32 s0, v4
	v_sub_u32_e32 v4, 0, v3
	v_rcp_iflag_f32_e32 v5, v5
	v_add_u32_e32 v6, s0, v2
	v_mul_f32_e32 v5, 0x4f7ffffe, v5
	v_cvt_u32_f32_e32 v5, v5
	v_mul_lo_u32 v2, v4, v5
	v_mul_hi_u32 v2, v5, v2
	v_add_u32_e32 v2, v5, v2
	v_mul_hi_u32 v2, v6, v2
	v_mul_lo_u32 v4, v2, v3
	v_sub_u32_e32 v4, v6, v4
	v_add_u32_e32 v5, 1, v2
	v_cmp_ge_u32_e32 vcc, v4, v3
	s_nop 1
	v_cndmask_b32_e32 v2, v2, v5, vcc
	v_sub_u32_e32 v5, v4, v3
	v_cndmask_b32_e32 v4, v4, v5, vcc
	v_add_u32_e32 v5, 1, v2
	v_cmp_ge_u32_e32 vcc, v4, v3
	v_add_u32_e32 v4, 1, v6
	s_nop 0
	v_cndmask_b32_e32 v2, v2, v5, vcc
	v_mul_lo_u32 v5, v3, v2
	v_add_u32_e32 v3, v5, v3
	v_cmp_ne_u32_e32 vcc, v4, v3
	s_and_saveexec_b64 s[0:1], vcc
	s_xor_b64 s[6:7], exec, s[0:1]
	s_cbranch_execz .LBB0_1220
	s_waitcnt lgkmcnt(0)
	v_readlane_b32 s12, v255, 2
	v_readlane_b32 s13, v255, 3
	v_mov_b32_e32 v1, 0
	s_add_u32 s12, s12, 0x7500
	s_addc_u32 s13, s13, 0
	global_load_dword v1, v1, s[12:13] sc1
	s_waitcnt vmcnt(0)
	v_cmp_eq_u32_e32 vcc, v1, v2
	s_and_saveexec_b64 s[8:9], vcc
	s_cbranch_execz .LBB0_1219
	v_readlane_b32 s0, v255, 2
	v_readlane_b32 s1, v255, 3
	s_add_u32 s10, s0, 0x4200
	s_addc_u32 s11, s1, 0
	s_mov_b32 s0, 1
	s_mov_b64 s[14:15], 0
	v_mov_b32_e32 v1, 0
	s_branch .LBB0_1210
